# code placement: s_nop padding so every 32-MFMA run of the six GEMM K-loops starts 8-byte aligned (plus pool + P12 LDS edits)
# baseline (speedup 1.0000x reference)
.LBB0_173:
	ds_read_b128 v[144:147], v155
	ds_read_b128 v[148:151], v155 offset:1024
	ds_read_b128 v[158:161], v155 offset:2048
	ds_read_b128 v[162:165], v155 offset:3072
	ds_read_b128 v[166:169], v156
	ds_read_b128 v[170:173], v156 offset:1024
	ds_read_b128 v[174:177], v156 offset:2048
	ds_read_b128 v[178:181], v156 offset:3072
	s_add_u32 s68, s66, 0xfff80080
	s_addc_u32 s69, s67, -1
	s_cmp_eq_u32 s77, 28
	s_cselect_b32 s71, s55, s69
	s_cselect_b32 s70, s59, s68
	s_cselect_b32 s69, s57, s76
	s_cselect_b32 s68, s65, s73
	v_lshl_add_u64 v[214:215], s[66:67], 0, v[136:137]
	s_add_i32 m0, s25, 0xc000
	ds_read_b128 v[182:185], v157
	ds_read_b128 v[186:189], v157 offset:1024
	ds_read_b128 v[190:193], v157 offset:2048
	ds_read_b128 v[194:197], v157 offset:3072
	ds_read_b128 v[198:201], v157 offset:4096
	ds_read_b128 v[202:205], v157 offset:5120
	ds_read_b128 v[206:209], v157 offset:6144
	ds_read_b128 v[210:213], v157 offset:7168
	global_load_lds_dwordx4 v[214:215], off
	v_lshl_add_u64 v[214:215], s[66:67], 0, v[138:139]
	s_add_i32 m0, s25, 0xe000
	s_nop 0
	global_load_lds_dwordx4 v[214:215], off
	s_waitcnt vmcnt(8)
	s_waitcnt lgkmcnt(0)
	s_barrier
	s_setprio 1
	s_waitcnt lgkmcnt(0)
	v_mfma_i32_16x16x64_i8 v[124:127], v[144:147], v[182:185], v[124:127]
	v_mfma_i32_16x16x64_i8 v[116:119], v[158:161], v[182:185], v[116:119]
	v_mfma_i32_16x16x64_i8 v[108:111], v[144:147], v[190:193], v[108:111]
	v_mfma_i32_16x16x64_i8 v[100:103], v[158:161], v[190:193], v[100:103]
	v_mfma_i32_16x16x64_i8 v[92:95], v[144:147], v[198:201], v[92:95]
	v_mfma_i32_16x16x64_i8 v[84:87], v[158:161], v[198:201], v[84:87]
	v_mfma_i32_16x16x64_i8 v[76:79], v[144:147], v[206:209], v[76:79]
	v_mfma_i32_16x16x64_i8 v[68:71], v[158:161], v[206:209], v[68:71]
	v_mfma_i32_16x16x64_i8 v[124:127], v[148:151], v[186:189], v[124:127]
	v_mfma_i32_16x16x64_i8 v[116:119], v[162:165], v[186:189], v[116:119]
	v_mfma_i32_16x16x64_i8 v[108:111], v[148:151], v[194:197], v[108:111]
	v_mfma_i32_16x16x64_i8 v[100:103], v[162:165], v[194:197], v[100:103]
	v_mfma_i32_16x16x64_i8 v[92:95], v[148:151], v[202:205], v[92:95]
	v_mfma_i32_16x16x64_i8 v[84:87], v[162:165], v[202:205], v[84:87]
	v_mfma_i32_16x16x64_i8 v[76:79], v[148:151], v[210:213], v[76:79]
	v_mfma_i32_16x16x64_i8 v[68:71], v[162:165], v[210:213], v[68:71]
	s_setprio 0
	s_setprio 1
	v_mfma_i32_16x16x64_i8 v[120:123], v[166:169], v[182:185], v[120:123]
	v_mfma_i32_16x16x64_i8 v[112:115], v[174:177], v[182:185], v[112:115]
	v_mfma_i32_16x16x64_i8 v[104:107], v[166:169], v[190:193], v[104:107]
	v_mfma_i32_16x16x64_i8 v[96:99], v[174:177], v[190:193], v[96:99]
	v_mfma_i32_16x16x64_i8 v[88:91], v[166:169], v[198:201], v[88:91]
	v_mfma_i32_16x16x64_i8 v[80:83], v[174:177], v[198:201], v[80:83]
	v_mfma_i32_16x16x64_i8 v[72:75], v[166:169], v[206:209], v[72:75]
	v_mfma_i32_16x16x64_i8 v[64:67], v[174:177], v[206:209], v[64:67]
	v_mfma_i32_16x16x64_i8 v[120:123], v[170:173], v[186:189], v[120:123]
	v_mfma_i32_16x16x64_i8 v[112:115], v[178:181], v[186:189], v[112:115]
	v_mfma_i32_16x16x64_i8 v[104:107], v[170:173], v[194:197], v[104:107]
	v_mfma_i32_16x16x64_i8 v[96:99], v[178:181], v[194:197], v[96:99]
	v_mfma_i32_16x16x64_i8 v[88:91], v[170:173], v[202:205], v[88:91]
	v_mfma_i32_16x16x64_i8 v[80:83], v[178:181], v[202:205], v[80:83]
	v_mfma_i32_16x16x64_i8 v[72:75], v[170:173], v[210:213], v[72:75]
	v_mfma_i32_16x16x64_i8 v[64:67], v[178:181], v[210:213], v[64:67]
	s_setprio 0
	s_barrier
	s_add_i32 s78, s35, s13
	v_lshl_add_u64 v[214:215], s[68:69], 0, v[132:133]
	s_mov_b32 m0, s78
	ds_read_b128 v[182:185], v157 offset:16384
	ds_read_b128 v[186:189], v157 offset:17408
	ds_read_b128 v[190:193], v157 offset:18432
	ds_read_b128 v[194:197], v157 offset:19456
	ds_read_b128 v[198:201], v157 offset:20480
	ds_read_b128 v[202:205], v157 offset:21504
	ds_read_b128 v[206:209], v157 offset:22528
	ds_read_b128 v[210:213], v157 offset:23552
	global_load_lds_dwordx4 v[214:215], off
	s_add_i32 m0, s78, 0x2000
	s_add_u32 s78, s68, 0x80000
	v_lshl_add_u64 v[216:217], s[68:69], 0, v[128:129]
	s_addc_u32 s79, s69, 0
	s_add_i32 s81, s52, s13
	global_load_lds_dwordx4 v[216:217], off
	v_lshl_add_u64 v[218:219], s[78:79], 0, v[132:133]
	s_mov_b32 m0, s81
	v_lshl_add_u64 v[220:221], s[70:71], 0, v[130:131]
	global_load_lds_dwordx4 v[218:219], off
	v_lshl_add_u64 v[218:219], s[78:79], 0, v[128:129]
	s_add_i32 m0, s81, 0x2000
	s_nop 0
	global_load_lds_dwordx4 v[218:219], off
	v_lshl_add_u64 v[218:219], s[70:71], 0, v[134:135]
	s_mov_b32 m0, s25
	s_nop 0
	global_load_lds_dwordx4 v[218:219], off
	s_mov_b32 m0, s26
	s_nop 0
	global_load_lds_dwordx4 v[220:221], off
	s_nop 0
	s_waitcnt vmcnt(8)
	s_waitcnt lgkmcnt(0)
	s_barrier
	s_setprio 1
	s_waitcnt lgkmcnt(0)
	v_mfma_i32_16x16x64_i8 v[60:63], v[144:147], v[182:185], v[60:63]
	v_mfma_i32_16x16x64_i8 v[52:55], v[158:161], v[182:185], v[52:55]
	v_mfma_i32_16x16x64_i8 v[44:47], v[144:147], v[190:193], v[44:47]
	v_mfma_i32_16x16x64_i8 v[36:39], v[158:161], v[190:193], v[36:39]
	v_mfma_i32_16x16x64_i8 v[28:31], v[144:147], v[198:201], v[28:31]
	v_mfma_i32_16x16x64_i8 v[20:23], v[158:161], v[198:201], v[20:23]
	v_mfma_i32_16x16x64_i8 v[12:15], v[144:147], v[206:209], v[12:15]
	v_mfma_i32_16x16x64_i8 v[4:7], v[158:161], v[206:209], v[4:7]
	v_mfma_i32_16x16x64_i8 v[60:63], v[148:151], v[186:189], v[60:63]
	v_mfma_i32_16x16x64_i8 v[52:55], v[162:165], v[186:189], v[52:55]
	v_mfma_i32_16x16x64_i8 v[44:47], v[148:151], v[194:197], v[44:47]
	v_mfma_i32_16x16x64_i8 v[36:39], v[162:165], v[194:197], v[36:39]
	v_mfma_i32_16x16x64_i8 v[28:31], v[148:151], v[202:205], v[28:31]
	v_mfma_i32_16x16x64_i8 v[20:23], v[162:165], v[202:205], v[20:23]
	v_mfma_i32_16x16x64_i8 v[12:15], v[148:151], v[210:213], v[12:15]
	v_mfma_i32_16x16x64_i8 v[4:7], v[162:165], v[210:213], v[4:7]
	s_setprio 0
	s_setprio 1
	v_mfma_i32_16x16x64_i8 v[56:59], v[166:169], v[182:185], v[56:59]
	v_mfma_i32_16x16x64_i8 v[48:51], v[174:177], v[182:185], v[48:51]
	v_mfma_i32_16x16x64_i8 v[40:43], v[166:169], v[190:193], v[40:43]
	v_mfma_i32_16x16x64_i8 v[32:35], v[174:177], v[190:193], v[32:35]
	v_mfma_i32_16x16x64_i8 v[24:27], v[166:169], v[198:201], v[24:27]
	v_mfma_i32_16x16x64_i8 v[16:19], v[174:177], v[198:201], v[16:19]
	v_mfma_i32_16x16x64_i8 v[8:11], v[166:169], v[206:209], v[8:11]
	v_mfma_i32_16x16x64_i8 v[0:3], v[174:177], v[206:209], v[0:3]
	v_mfma_i32_16x16x64_i8 v[56:59], v[170:173], v[186:189], v[56:59]
	v_mfma_i32_16x16x64_i8 v[48:51], v[178:181], v[186:189], v[48:51]
	v_mfma_i32_16x16x64_i8 v[40:43], v[170:173], v[194:197], v[40:43]
	v_mfma_i32_16x16x64_i8 v[32:35], v[178:181], v[194:197], v[32:35]
	v_mfma_i32_16x16x64_i8 v[24:27], v[170:173], v[202:205], v[24:27]
	v_mfma_i32_16x16x64_i8 v[16:19], v[178:181], v[202:205], v[16:19]
	v_mfma_i32_16x16x64_i8 v[8:11], v[170:173], v[210:213], v[8:11]
	v_mfma_i32_16x16x64_i8 v[0:3], v[178:181], v[210:213], v[0:3]
	s_setprio 0
	s_barrier
	s_add_i32 s78, 0, 0x18000
	s_add_i32 s79, 0, 0x1c000
	v_add_u32_e32 v162, s78, v153
	v_add_u32_e32 v178, s79, v153
	ds_read_b128 v[144:147], v162
	ds_read_b128 v[148:151], v162 offset:1024
	ds_read_b128 v[158:161], v162 offset:2048
	ds_read_b128 v[162:165], v162 offset:3072
	ds_read_b128 v[166:169], v178
	ds_read_b128 v[170:173], v178 offset:1024
	ds_read_b128 v[174:177], v178 offset:2048
	ds_read_b128 v[178:181], v178 offset:3072
	s_add_u32 s70, s70, 0x80000
	s_addc_u32 s71, s71, 0
	s_mov_b32 m0, s27
	v_lshl_add_u64 v[222:223], s[70:71], 0, v[134:135]
	ds_read_b128 v[182:185], v157 offset:32768
	ds_read_b128 v[186:189], v157 offset:33792
	ds_read_b128 v[190:193], v157 offset:34816
	ds_read_b128 v[194:197], v157 offset:35840
	ds_read_b128 v[198:201], v157 offset:36864
	ds_read_b128 v[202:205], v157 offset:37888
	ds_read_b128 v[206:209], v157 offset:38912
	ds_read_b128 v[210:213], v157 offset:39936
	global_load_lds_dwordx4 v[222:223], off
	v_lshl_add_u64 v[222:223], s[70:71], 0, v[130:131]
	s_mov_b32 m0, s28
	s_nop 0
	global_load_lds_dwordx4 v[222:223], off
	s_nop 0
	s_waitcnt vmcnt(8)
	s_waitcnt lgkmcnt(0)
	s_barrier
	s_setprio 1
	s_waitcnt lgkmcnt(0)
	v_mfma_i32_16x16x64_i8 v[124:127], v[144:147], v[182:185], v[124:127]
	v_mfma_i32_16x16x64_i8 v[116:119], v[158:161], v[182:185], v[116:119]
	v_mfma_i32_16x16x64_i8 v[108:111], v[144:147], v[190:193], v[108:111]
	v_mfma_i32_16x16x64_i8 v[100:103], v[158:161], v[190:193], v[100:103]
	v_mfma_i32_16x16x64_i8 v[92:95], v[144:147], v[198:201], v[92:95]
	v_mfma_i32_16x16x64_i8 v[84:87], v[158:161], v[198:201], v[84:87]
	v_mfma_i32_16x16x64_i8 v[76:79], v[144:147], v[206:209], v[76:79]
	v_mfma_i32_16x16x64_i8 v[68:71], v[158:161], v[206:209], v[68:71]
	v_mfma_i32_16x16x64_i8 v[124:127], v[148:151], v[186:189], v[124:127]
	v_mfma_i32_16x16x64_i8 v[116:119], v[162:165], v[186:189], v[116:119]
	v_mfma_i32_16x16x64_i8 v[108:111], v[148:151], v[194:197], v[108:111]
	v_mfma_i32_16x16x64_i8 v[100:103], v[162:165], v[194:197], v[100:103]
	v_mfma_i32_16x16x64_i8 v[92:95], v[148:151], v[202:205], v[92:95]
	v_mfma_i32_16x16x64_i8 v[84:87], v[162:165], v[202:205], v[84:87]
	v_mfma_i32_16x16x64_i8 v[76:79], v[148:151], v[210:213], v[76:79]
	v_mfma_i32_16x16x64_i8 v[68:71], v[162:165], v[210:213], v[68:71]
	s_setprio 0
	s_setprio 1
	v_mfma_i32_16x16x64_i8 v[120:123], v[166:169], v[182:185], v[120:123]
	v_mfma_i32_16x16x64_i8 v[112:115], v[174:177], v[182:185], v[112:115]
	v_mfma_i32_16x16x64_i8 v[104:107], v[166:169], v[190:193], v[104:107]
	v_mfma_i32_16x16x64_i8 v[96:99], v[174:177], v[190:193], v[96:99]
	v_mfma_i32_16x16x64_i8 v[88:91], v[166:169], v[198:201], v[88:91]
	v_mfma_i32_16x16x64_i8 v[80:83], v[174:177], v[198:201], v[80:83]
	v_mfma_i32_16x16x64_i8 v[72:75], v[166:169], v[206:209], v[72:75]
	v_mfma_i32_16x16x64_i8 v[64:67], v[174:177], v[206:209], v[64:67]
	v_mfma_i32_16x16x64_i8 v[120:123], v[170:173], v[186:189], v[120:123]
	v_mfma_i32_16x16x64_i8 v[112:115], v[178:181], v[186:189], v[112:115]
	v_mfma_i32_16x16x64_i8 v[104:107], v[170:173], v[194:197], v[104:107]
	v_mfma_i32_16x16x64_i8 v[96:99], v[178:181], v[194:197], v[96:99]
	v_mfma_i32_16x16x64_i8 v[88:91], v[170:173], v[202:205], v[88:91]
	v_mfma_i32_16x16x64_i8 v[80:83], v[178:181], v[202:205], v[80:83]
	v_mfma_i32_16x16x64_i8 v[72:75], v[170:173], v[210:213], v[72:75]
	v_mfma_i32_16x16x64_i8 v[64:67], v[178:181], v[210:213], v[64:67]
	s_setprio 0
	s_barrier
	s_add_i32 s70, s78, s13
	v_lshl_add_u64 v[214:215], v[214:215], 0, s[14:15]
	s_mov_b32 m0, s70
	ds_read_b128 v[182:185], v157 offset:49152
	ds_read_b128 v[186:189], v157 offset:50176
	ds_read_b128 v[190:193], v157 offset:51200
	ds_read_b128 v[194:197], v157 offset:52224
	ds_read_b128 v[198:201], v157 offset:53248
	ds_read_b128 v[202:205], v157 offset:54272
	ds_read_b128 v[206:209], v157 offset:55296
	ds_read_b128 v[210:213], v157 offset:56320
	global_load_lds_dwordx4 v[214:215], off
	s_add_i32 m0, s70, 0x2000
	s_add_u32 s68, s68, 0x80080
	v_lshl_add_u64 v[214:215], v[216:217], 0, s[14:15]
	s_addc_u32 s69, s69, 0
	s_add_i32 s70, s79, s13
	global_load_lds_dwordx4 v[214:215], off
	v_lshl_add_u64 v[214:215], s[68:69], 0, v[132:133]
	s_mov_b32 m0, s70
	s_nop 0
	global_load_lds_dwordx4 v[214:215], off
	v_lshl_add_u64 v[214:215], s[68:69], 0, v[128:129]
	s_add_i32 m0, s70, 0x2000
	s_nop 0
	global_load_lds_dwordx4 v[214:215], off
	v_lshl_add_u64 v[214:215], v[218:219], 0, s[14:15]
	s_mov_b32 m0, s31
	s_nop 0
	global_load_lds_dwordx4 v[214:215], off
	v_lshl_add_u64 v[214:215], v[220:221], 0, s[14:15]
	s_mov_b32 m0, s33
	s_nop 0
	global_load_lds_dwordx4 v[214:215], off
	s_waitcnt vmcnt(8)
	s_waitcnt lgkmcnt(0)
	s_barrier
	s_setprio 1
	s_waitcnt lgkmcnt(0)
	v_mfma_i32_16x16x64_i8 v[60:63], v[144:147], v[182:185], v[60:63]
	v_mfma_i32_16x16x64_i8 v[52:55], v[158:161], v[182:185], v[52:55]
	v_mfma_i32_16x16x64_i8 v[44:47], v[144:147], v[190:193], v[44:47]
	v_mfma_i32_16x16x64_i8 v[36:39], v[158:161], v[190:193], v[36:39]
	v_mfma_i32_16x16x64_i8 v[28:31], v[144:147], v[198:201], v[28:31]
	v_mfma_i32_16x16x64_i8 v[20:23], v[158:161], v[198:201], v[20:23]
	v_mfma_i32_16x16x64_i8 v[12:15], v[144:147], v[206:209], v[12:15]
	v_mfma_i32_16x16x64_i8 v[4:7], v[158:161], v[206:209], v[4:7]
	v_mfma_i32_16x16x64_i8 v[60:63], v[148:151], v[186:189], v[60:63]
	v_mfma_i32_16x16x64_i8 v[52:55], v[162:165], v[186:189], v[52:55]
	v_mfma_i32_16x16x64_i8 v[44:47], v[148:151], v[194:197], v[44:47]
	v_mfma_i32_16x16x64_i8 v[36:39], v[162:165], v[194:197], v[36:39]
	v_mfma_i32_16x16x64_i8 v[28:31], v[148:151], v[202:205], v[28:31]
	v_mfma_i32_16x16x64_i8 v[20:23], v[162:165], v[202:205], v[20:23]
	v_mfma_i32_16x16x64_i8 v[12:15], v[148:151], v[210:213], v[12:15]
	v_mfma_i32_16x16x64_i8 v[4:7], v[162:165], v[210:213], v[4:7]
	s_setprio 0
	s_setprio 1
	v_mfma_i32_16x16x64_i8 v[56:59], v[166:169], v[182:185], v[56:59]
	v_mfma_i32_16x16x64_i8 v[48:51], v[174:177], v[182:185], v[48:51]
	v_mfma_i32_16x16x64_i8 v[40:43], v[166:169], v[190:193], v[40:43]
	v_mfma_i32_16x16x64_i8 v[32:35], v[174:177], v[190:193], v[32:35]
	v_mfma_i32_16x16x64_i8 v[24:27], v[166:169], v[198:201], v[24:27]
	v_mfma_i32_16x16x64_i8 v[16:19], v[174:177], v[198:201], v[16:19]
	v_mfma_i32_16x16x64_i8 v[8:11], v[166:169], v[206:209], v[8:11]
	v_mfma_i32_16x16x64_i8 v[0:3], v[174:177], v[206:209], v[0:3]
	v_mfma_i32_16x16x64_i8 v[56:59], v[170:173], v[186:189], v[56:59]
	v_mfma_i32_16x16x64_i8 v[48:51], v[178:181], v[186:189], v[48:51]
	v_mfma_i32_16x16x64_i8 v[40:43], v[170:173], v[194:197], v[40:43]
	v_mfma_i32_16x16x64_i8 v[32:35], v[178:181], v[194:197], v[32:35]
	v_mfma_i32_16x16x64_i8 v[24:27], v[170:173], v[202:205], v[24:27]
	v_mfma_i32_16x16x64_i8 v[16:19], v[178:181], v[202:205], v[16:19]
	v_mfma_i32_16x16x64_i8 v[8:11], v[170:173], v[210:213], v[8:11]
	v_mfma_i32_16x16x64_i8 v[0:3], v[178:181], v[210:213], v[0:3]
	s_setprio 0
	s_barrier
	s_add_i32 s77, s77, 2
	s_add_u32 s66, s66, 0x100
	s_addc_u32 s67, s67, 0
	s_add_u32 s73, s73, 0x100
	s_addc_u32 s76, s76, 0
	s_cmp_gt_u32 s77, 29
	s_cbranch_scc0 .LBB0_173
	s_and_b64 vcc, exec, s[20:21]
	s_cbranch_vccz .LBB0_176
	s_barrier

.LBB0_258:
	ds_read_b128 v[152:155], v149
	ds_read_b128 v[156:159], v149 offset:1024
	ds_read_b128 v[160:163], v149 offset:2048
	ds_read_b128 v[164:167], v149 offset:3072
	ds_read_b128 v[168:171], v150
	ds_read_b128 v[172:175], v150 offset:1024
	ds_read_b128 v[176:179], v150 offset:2048
	ds_read_b128 v[180:183], v150 offset:3072
	s_add_u32 s36, s22, 0x100
	s_addc_u32 s37, s23, 0
	s_cmpk_eq_i32 s62, 0xa8
	s_cselect_b32 s57, s5, s37
	s_cselect_b32 s56, s4, s36
	s_cselect_b32 s41, s21, s61
	s_cselect_b32 s40, s20, s60
	v_lshl_add_u64 v[144:145], s[22:23], 0, v[136:137]
	s_add_i32 m0, s25, 0xc000
	ds_read_b128 v[184:187], v151
	ds_read_b128 v[188:191], v151 offset:1024
	ds_read_b128 v[192:195], v151 offset:2048
	ds_read_b128 v[196:199], v151 offset:3072
	ds_read_b128 v[200:203], v151 offset:4096
	ds_read_b128 v[204:207], v151 offset:5120
	ds_read_b128 v[208:211], v151 offset:6144
	ds_read_b128 v[212:215], v151 offset:7168
	global_load_lds_dwordx4 v[144:145], off
	v_lshl_add_u64 v[144:145], s[22:23], 0, v[138:139]
	s_add_i32 m0, s25, 0xe000
	s_nop 0
	global_load_lds_dwordx4 v[144:145], off
	s_nop 0
	s_waitcnt vmcnt(8)
	s_waitcnt lgkmcnt(0)
	s_barrier
	s_setprio 1
	s_waitcnt lgkmcnt(0)
	v_mfma_f32_16x16x32_bf16 v[124:127], v[152:155], v[184:187], v[124:127]
	v_mfma_f32_16x16x32_bf16 v[120:123], v[160:163], v[184:187], v[120:123]
	v_mfma_f32_16x16x32_bf16 v[116:119], v[152:155], v[192:195], v[116:119]
	v_mfma_f32_16x16x32_bf16 v[108:111], v[160:163], v[192:195], v[108:111]
	v_mfma_f32_16x16x32_bf16 v[100:103], v[152:155], v[200:203], v[100:103]
	v_mfma_f32_16x16x32_bf16 v[92:95], v[160:163], v[200:203], v[92:95]
	v_mfma_f32_16x16x32_bf16 v[84:87], v[152:155], v[208:211], v[84:87]
	v_mfma_f32_16x16x32_bf16 v[76:79], v[160:163], v[208:211], v[76:79]
	v_mfma_f32_16x16x32_bf16 v[124:127], v[156:159], v[188:191], v[124:127]
	v_mfma_f32_16x16x32_bf16 v[120:123], v[164:167], v[188:191], v[120:123]
	v_mfma_f32_16x16x32_bf16 v[116:119], v[156:159], v[196:199], v[116:119]
	v_mfma_f32_16x16x32_bf16 v[108:111], v[164:167], v[196:199], v[108:111]
	v_mfma_f32_16x16x32_bf16 v[100:103], v[156:159], v[204:207], v[100:103]
	v_mfma_f32_16x16x32_bf16 v[92:95], v[164:167], v[204:207], v[92:95]
	v_mfma_f32_16x16x32_bf16 v[84:87], v[156:159], v[212:215], v[84:87]
	v_mfma_f32_16x16x32_bf16 v[76:79], v[164:167], v[212:215], v[76:79]
	s_setprio 0
	s_setprio 1
	v_mfma_f32_16x16x32_bf16 v[112:115], v[168:171], v[184:187], v[112:115]
	v_mfma_f32_16x16x32_bf16 v[104:107], v[176:179], v[184:187], v[104:107]
	v_mfma_f32_16x16x32_bf16 v[96:99], v[168:171], v[192:195], v[96:99]
	v_mfma_f32_16x16x32_bf16 v[88:91], v[176:179], v[192:195], v[88:91]
	v_mfma_f32_16x16x32_bf16 v[80:83], v[168:171], v[200:203], v[80:83]
	v_mfma_f32_16x16x32_bf16 v[72:75], v[176:179], v[200:203], v[72:75]
	v_mfma_f32_16x16x32_bf16 v[68:71], v[168:171], v[208:211], v[68:71]
	v_mfma_f32_16x16x32_bf16 v[64:67], v[176:179], v[208:211], v[64:67]
	v_mfma_f32_16x16x32_bf16 v[112:115], v[172:175], v[188:191], v[112:115]
	v_mfma_f32_16x16x32_bf16 v[104:107], v[180:183], v[188:191], v[104:107]
	v_mfma_f32_16x16x32_bf16 v[96:99], v[172:175], v[196:199], v[96:99]
	v_mfma_f32_16x16x32_bf16 v[88:91], v[180:183], v[196:199], v[88:91]
	v_mfma_f32_16x16x32_bf16 v[80:83], v[172:175], v[204:207], v[80:83]
	v_mfma_f32_16x16x32_bf16 v[72:75], v[180:183], v[204:207], v[72:75]
	v_mfma_f32_16x16x32_bf16 v[68:71], v[172:175], v[212:215], v[68:71]
	v_mfma_f32_16x16x32_bf16 v[64:67], v[180:183], v[212:215], v[64:67]
	s_setprio 0
	s_barrier
	s_add_i32 s22, s35, s3
	v_lshl_add_u64 v[144:145], s[40:41], 0, v[132:133]
	s_mov_b32 m0, s22
	ds_read_b128 v[184:187], v151 offset:16384
	ds_read_b128 v[188:191], v151 offset:17408
	ds_read_b128 v[192:195], v151 offset:18432
	ds_read_b128 v[196:199], v151 offset:19456
	ds_read_b128 v[200:203], v151 offset:20480
	ds_read_b128 v[204:207], v151 offset:21504
	ds_read_b128 v[208:211], v151 offset:22528
	ds_read_b128 v[212:215], v151 offset:23552
	global_load_lds_dwordx4 v[144:145], off
	s_add_i32 m0, s22, 0x2000
	s_add_u32 s22, s40, 0x2b0000
	v_lshl_add_u64 v[216:217], s[40:41], 0, v[128:129]
	s_addc_u32 s23, s41, 0
	s_add_i32 s63, s52, s3
	global_load_lds_dwordx4 v[216:217], off
	v_lshl_add_u64 v[218:219], s[22:23], 0, v[132:133]
	s_mov_b32 m0, s63
	v_lshl_add_u64 v[220:221], s[56:57], 0, v[130:131]
	global_load_lds_dwordx4 v[218:219], off
	v_lshl_add_u64 v[218:219], s[22:23], 0, v[128:129]
	s_add_i32 m0, s63, 0x2000
	s_nop 0
	global_load_lds_dwordx4 v[218:219], off
	v_lshl_add_u64 v[218:219], s[56:57], 0, v[134:135]
	s_mov_b32 m0, s25
	s_nop 0
	global_load_lds_dwordx4 v[218:219], off
	s_mov_b32 m0, s26
	s_nop 0
	global_load_lds_dwordx4 v[220:221], off
	s_nop 0
	s_waitcnt vmcnt(8)
	s_waitcnt lgkmcnt(0)
	s_barrier
	s_setprio 1
	s_waitcnt lgkmcnt(0)
	v_mfma_f32_16x16x32_bf16 v[60:63], v[152:155], v[184:187], v[60:63]
	v_mfma_f32_16x16x32_bf16 v[56:59], v[160:163], v[184:187], v[56:59]
	v_mfma_f32_16x16x32_bf16 v[52:55], v[152:155], v[192:195], v[52:55]
	v_mfma_f32_16x16x32_bf16 v[44:47], v[160:163], v[192:195], v[44:47]
	v_mfma_f32_16x16x32_bf16 v[36:39], v[152:155], v[200:203], v[36:39]
	v_mfma_f32_16x16x32_bf16 v[28:31], v[160:163], v[200:203], v[28:31]
	v_mfma_f32_16x16x32_bf16 v[20:23], v[152:155], v[208:211], v[20:23]
	v_mfma_f32_16x16x32_bf16 v[12:15], v[160:163], v[208:211], v[12:15]
	v_mfma_f32_16x16x32_bf16 v[60:63], v[156:159], v[188:191], v[60:63]
	v_mfma_f32_16x16x32_bf16 v[56:59], v[164:167], v[188:191], v[56:59]
	v_mfma_f32_16x16x32_bf16 v[52:55], v[156:159], v[196:199], v[52:55]
	v_mfma_f32_16x16x32_bf16 v[44:47], v[164:167], v[196:199], v[44:47]
	v_mfma_f32_16x16x32_bf16 v[36:39], v[156:159], v[204:207], v[36:39]
	v_mfma_f32_16x16x32_bf16 v[28:31], v[164:167], v[204:207], v[28:31]
	v_mfma_f32_16x16x32_bf16 v[20:23], v[156:159], v[212:215], v[20:23]
	v_mfma_f32_16x16x32_bf16 v[12:15], v[164:167], v[212:215], v[12:15]
	s_setprio 0
	s_setprio 1
	v_mfma_f32_16x16x32_bf16 v[48:51], v[168:171], v[184:187], v[48:51]
	v_mfma_f32_16x16x32_bf16 v[40:43], v[176:179], v[184:187], v[40:43]
	v_mfma_f32_16x16x32_bf16 v[32:35], v[168:171], v[192:195], v[32:35]
	v_mfma_f32_16x16x32_bf16 v[24:27], v[176:179], v[192:195], v[24:27]
	v_mfma_f32_16x16x32_bf16 v[16:19], v[168:171], v[200:203], v[16:19]
	v_mfma_f32_16x16x32_bf16 v[8:11], v[176:179], v[200:203], v[8:11]
	v_mfma_f32_16x16x32_bf16 v[4:7], v[168:171], v[208:211], v[4:7]
	v_mfma_f32_16x16x32_bf16 v[0:3], v[176:179], v[208:211], v[0:3]
	v_mfma_f32_16x16x32_bf16 v[48:51], v[172:175], v[188:191], v[48:51]
	v_mfma_f32_16x16x32_bf16 v[40:43], v[180:183], v[188:191], v[40:43]
	v_mfma_f32_16x16x32_bf16 v[32:35], v[172:175], v[196:199], v[32:35]
	v_mfma_f32_16x16x32_bf16 v[24:27], v[180:183], v[196:199], v[24:27]
	v_mfma_f32_16x16x32_bf16 v[16:19], v[172:175], v[204:207], v[16:19]
	v_mfma_f32_16x16x32_bf16 v[8:11], v[180:183], v[204:207], v[8:11]
	v_mfma_f32_16x16x32_bf16 v[4:7], v[172:175], v[212:215], v[4:7]
	v_mfma_f32_16x16x32_bf16 v[0:3], v[180:183], v[212:215], v[0:3]
	s_setprio 0
	s_barrier
	s_add_i32 s63, 0, 0x18000
	s_add_i32 s64, 0, 0x1c000
	v_add_u32_e32 v164, s63, v147
	v_add_u32_e32 v180, s64, v147
	ds_read_b128 v[152:155], v164
	ds_read_b128 v[156:159], v164 offset:1024
	ds_read_b128 v[160:163], v164 offset:2048
	ds_read_b128 v[164:167], v164 offset:3072
	ds_read_b128 v[168:171], v180
	ds_read_b128 v[172:175], v180 offset:1024
	ds_read_b128 v[176:179], v180 offset:2048
	ds_read_b128 v[180:183], v180 offset:3072
	s_add_u32 s22, s56, 0x2b0000
	s_addc_u32 s23, s57, 0
	s_mov_b32 m0, s27
	v_lshl_add_u64 v[222:223], s[22:23], 0, v[134:135]
	ds_read_b128 v[184:187], v151 offset:32768
	ds_read_b128 v[188:191], v151 offset:33792
	ds_read_b128 v[192:195], v151 offset:34816
	ds_read_b128 v[196:199], v151 offset:35840
	ds_read_b128 v[200:203], v151 offset:36864
	ds_read_b128 v[204:207], v151 offset:37888
	ds_read_b128 v[208:211], v151 offset:38912
	ds_read_b128 v[212:215], v151 offset:39936
	global_load_lds_dwordx4 v[222:223], off
	v_lshl_add_u64 v[222:223], s[22:23], 0, v[130:131]
	s_mov_b32 m0, s28
	s_nop 0
	global_load_lds_dwordx4 v[222:223], off
	s_nop 0
	s_waitcnt vmcnt(8)
	s_waitcnt lgkmcnt(0)
	s_barrier
	s_setprio 1
	s_waitcnt lgkmcnt(0)
	v_mfma_f32_16x16x32_bf16 v[124:127], v[152:155], v[184:187], v[124:127]
	v_mfma_f32_16x16x32_bf16 v[120:123], v[160:163], v[184:187], v[120:123]
	v_mfma_f32_16x16x32_bf16 v[116:119], v[152:155], v[192:195], v[116:119]
	v_mfma_f32_16x16x32_bf16 v[108:111], v[160:163], v[192:195], v[108:111]
	v_mfma_f32_16x16x32_bf16 v[100:103], v[152:155], v[200:203], v[100:103]
	v_mfma_f32_16x16x32_bf16 v[92:95], v[160:163], v[200:203], v[92:95]
	v_mfma_f32_16x16x32_bf16 v[84:87], v[152:155], v[208:211], v[84:87]
	v_mfma_f32_16x16x32_bf16 v[76:79], v[160:163], v[208:211], v[76:79]
	v_mfma_f32_16x16x32_bf16 v[124:127], v[156:159], v[188:191], v[124:127]
	v_mfma_f32_16x16x32_bf16 v[120:123], v[164:167], v[188:191], v[120:123]
	v_mfma_f32_16x16x32_bf16 v[116:119], v[156:159], v[196:199], v[116:119]
	v_mfma_f32_16x16x32_bf16 v[108:111], v[164:167], v[196:199], v[108:111]
	v_mfma_f32_16x16x32_bf16 v[100:103], v[156:159], v[204:207], v[100:103]
	v_mfma_f32_16x16x32_bf16 v[92:95], v[164:167], v[204:207], v[92:95]
	v_mfma_f32_16x16x32_bf16 v[84:87], v[156:159], v[212:215], v[84:87]
	v_mfma_f32_16x16x32_bf16 v[76:79], v[164:167], v[212:215], v[76:79]
	s_setprio 0
	s_setprio 1
	v_mfma_f32_16x16x32_bf16 v[112:115], v[168:171], v[184:187], v[112:115]
	v_mfma_f32_16x16x32_bf16 v[104:107], v[176:179], v[184:187], v[104:107]
	v_mfma_f32_16x16x32_bf16 v[96:99], v[168:171], v[192:195], v[96:99]
	v_mfma_f32_16x16x32_bf16 v[88:91], v[176:179], v[192:195], v[88:91]
	v_mfma_f32_16x16x32_bf16 v[80:83], v[168:171], v[200:203], v[80:83]
	v_mfma_f32_16x16x32_bf16 v[72:75], v[176:179], v[200:203], v[72:75]
	v_mfma_f32_16x16x32_bf16 v[68:71], v[168:171], v[208:211], v[68:71]
	v_mfma_f32_16x16x32_bf16 v[64:67], v[176:179], v[208:211], v[64:67]
	v_mfma_f32_16x16x32_bf16 v[112:115], v[172:175], v[188:191], v[112:115]
	v_mfma_f32_16x16x32_bf16 v[104:107], v[180:183], v[188:191], v[104:107]
	v_mfma_f32_16x16x32_bf16 v[96:99], v[172:175], v[196:199], v[96:99]
	v_mfma_f32_16x16x32_bf16 v[88:91], v[180:183], v[196:199], v[88:91]
	v_mfma_f32_16x16x32_bf16 v[80:83], v[172:175], v[204:207], v[80:83]
	v_mfma_f32_16x16x32_bf16 v[72:75], v[180:183], v[204:207], v[72:75]
	v_mfma_f32_16x16x32_bf16 v[68:71], v[172:175], v[212:215], v[68:71]
	v_mfma_f32_16x16x32_bf16 v[64:67], v[180:183], v[212:215], v[64:67]
	s_setprio 0
	s_barrier
	s_add_i32 s22, s63, s3
	v_lshl_add_u64 v[144:145], v[144:145], 0, s[12:13]
	s_mov_b32 m0, s22
	ds_read_b128 v[184:187], v151 offset:49152
	ds_read_b128 v[188:191], v151 offset:50176
	ds_read_b128 v[192:195], v151 offset:51200
	ds_read_b128 v[196:199], v151 offset:52224
	ds_read_b128 v[200:203], v151 offset:53248
	ds_read_b128 v[204:207], v151 offset:54272
	ds_read_b128 v[208:211], v151 offset:55296
	ds_read_b128 v[212:215], v151 offset:56320
	global_load_lds_dwordx4 v[144:145], off
	s_add_i32 m0, s22, 0x2000
	s_add_u32 s22, s40, 0x2b0080
	v_lshl_add_u64 v[144:145], v[216:217], 0, s[12:13]
	s_addc_u32 s23, s41, 0
	s_add_i32 s40, s64, s3
	global_load_lds_dwordx4 v[144:145], off
	v_lshl_add_u64 v[144:145], s[22:23], 0, v[132:133]
	s_mov_b32 m0, s40
	s_nop 0
	global_load_lds_dwordx4 v[144:145], off
	v_lshl_add_u64 v[144:145], s[22:23], 0, v[128:129]
	s_add_i32 m0, s40, 0x2000
	s_nop 0
	global_load_lds_dwordx4 v[144:145], off
	v_lshl_add_u64 v[144:145], v[218:219], 0, s[12:13]
	s_mov_b32 m0, s31
	s_nop 0
	global_load_lds_dwordx4 v[144:145], off
	v_lshl_add_u64 v[144:145], v[220:221], 0, s[12:13]
	s_mov_b32 m0, s33
	s_nop 0
	global_load_lds_dwordx4 v[144:145], off
	s_waitcnt vmcnt(8)
	s_waitcnt lgkmcnt(0)
	s_barrier
	s_setprio 1
	s_waitcnt lgkmcnt(0)
	v_mfma_f32_16x16x32_bf16 v[60:63], v[152:155], v[184:187], v[60:63]
	v_mfma_f32_16x16x32_bf16 v[56:59], v[160:163], v[184:187], v[56:59]
	v_mfma_f32_16x16x32_bf16 v[52:55], v[152:155], v[192:195], v[52:55]
	v_mfma_f32_16x16x32_bf16 v[44:47], v[160:163], v[192:195], v[44:47]
	v_mfma_f32_16x16x32_bf16 v[36:39], v[152:155], v[200:203], v[36:39]
	v_mfma_f32_16x16x32_bf16 v[28:31], v[160:163], v[200:203], v[28:31]
	v_mfma_f32_16x16x32_bf16 v[20:23], v[152:155], v[208:211], v[20:23]
	v_mfma_f32_16x16x32_bf16 v[12:15], v[160:163], v[208:211], v[12:15]
	v_mfma_f32_16x16x32_bf16 v[60:63], v[156:159], v[188:191], v[60:63]
	v_mfma_f32_16x16x32_bf16 v[56:59], v[164:167], v[188:191], v[56:59]
	v_mfma_f32_16x16x32_bf16 v[52:55], v[156:159], v[196:199], v[52:55]
	v_mfma_f32_16x16x32_bf16 v[44:47], v[164:167], v[196:199], v[44:47]
	v_mfma_f32_16x16x32_bf16 v[36:39], v[156:159], v[204:207], v[36:39]
	v_mfma_f32_16x16x32_bf16 v[28:31], v[164:167], v[204:207], v[28:31]
	v_mfma_f32_16x16x32_bf16 v[20:23], v[156:159], v[212:215], v[20:23]
	v_mfma_f32_16x16x32_bf16 v[12:15], v[164:167], v[212:215], v[12:15]
	s_setprio 0
	s_setprio 1
	v_mfma_f32_16x16x32_bf16 v[48:51], v[168:171], v[184:187], v[48:51]
	v_mfma_f32_16x16x32_bf16 v[40:43], v[176:179], v[184:187], v[40:43]
	v_mfma_f32_16x16x32_bf16 v[32:35], v[168:171], v[192:195], v[32:35]
	v_mfma_f32_16x16x32_bf16 v[24:27], v[176:179], v[192:195], v[24:27]
	v_mfma_f32_16x16x32_bf16 v[16:19], v[168:171], v[200:203], v[16:19]
	v_mfma_f32_16x16x32_bf16 v[8:11], v[176:179], v[200:203], v[8:11]
	v_mfma_f32_16x16x32_bf16 v[4:7], v[168:171], v[208:211], v[4:7]
	v_mfma_f32_16x16x32_bf16 v[0:3], v[176:179], v[208:211], v[0:3]
	v_mfma_f32_16x16x32_bf16 v[48:51], v[172:175], v[188:191], v[48:51]
	v_mfma_f32_16x16x32_bf16 v[40:43], v[180:183], v[188:191], v[40:43]
	v_mfma_f32_16x16x32_bf16 v[32:35], v[172:175], v[196:199], v[32:35]
	v_mfma_f32_16x16x32_bf16 v[24:27], v[180:183], v[196:199], v[24:27]
	v_mfma_f32_16x16x32_bf16 v[16:19], v[172:175], v[204:207], v[16:19]
	v_mfma_f32_16x16x32_bf16 v[8:11], v[180:183], v[204:207], v[8:11]
	v_mfma_f32_16x16x32_bf16 v[4:7], v[172:175], v[212:215], v[4:7]
	v_mfma_f32_16x16x32_bf16 v[0:3], v[180:183], v[212:215], v[0:3]
	s_setprio 0
	s_barrier
	s_add_i32 s62, s62, 2
	s_add_u32 s60, s60, 0x100
	s_addc_u32 s61, s61, 0
	s_cmpk_gt_u32 s62, 0xa9
	s_mov_b64 s[22:23], s[36:37]
	s_cbranch_scc0 .LBB0_258
	s_and_b64 vcc, exec, s[14:15]
	s_cbranch_vccz .LBB0_261
	s_barrier

.LBB0_394:
	ds_read_b128 v[156:159], v152
	ds_read_b128 v[160:163], v152 offset:1024
	ds_read_b128 v[164:167], v152 offset:2048
	ds_read_b128 v[168:171], v152 offset:3072
	ds_read_b128 v[172:175], v153
	ds_read_b128 v[176:179], v153 offset:1024
	ds_read_b128 v[180:183], v153 offset:2048
	ds_read_b128 v[184:187], v153 offset:3072
	s_add_u32 s40, s38, 0xfff00080
	s_addc_u32 s41, s39, -1
	s_cmp_eq_u32 s64, 60
	s_cselect_b32 s57, s21, s41
	s_cselect_b32 s56, s60, s40
	s_cselect_b32 s41, s15, s63
	s_cselect_b32 s40, s61, s62
	v_lshl_add_u64 v[148:149], s[38:39], 0, v[140:141]
	s_add_i32 m0, s29, 0xc000
	ds_read_b128 v[188:191], v154
	ds_read_b128 v[192:195], v154 offset:1024
	ds_read_b128 v[196:199], v154 offset:2048
	ds_read_b128 v[200:203], v154 offset:3072
	ds_read_b128 v[204:207], v154 offset:4096
	ds_read_b128 v[208:211], v154 offset:5120
	ds_read_b128 v[212:215], v154 offset:6144
	ds_read_b128 v[216:219], v154 offset:7168
	global_load_lds_dwordx4 v[148:149], off
	v_lshl_add_u64 v[148:149], s[38:39], 0, v[142:143]
	s_add_i32 m0, s29, 0xe000
	s_nop 0
	global_load_lds_dwordx4 v[148:149], off
	s_waitcnt vmcnt(8)
	s_waitcnt lgkmcnt(0)
	s_barrier
	s_setprio 1
	s_waitcnt lgkmcnt(0)
	v_mfma_f32_16x16x32_bf16 v[124:127], v[156:159], v[188:191], v[124:127]
	v_mfma_f32_16x16x32_bf16 v[120:123], v[164:167], v[188:191], v[120:123]
	v_mfma_f32_16x16x32_bf16 v[112:115], v[156:159], v[196:199], v[112:115]
	v_mfma_f32_16x16x32_bf16 v[104:107], v[164:167], v[196:199], v[104:107]
	v_mfma_f32_16x16x32_bf16 v[96:99], v[156:159], v[204:207], v[96:99]
	v_mfma_f32_16x16x32_bf16 v[88:91], v[164:167], v[204:207], v[88:91]
	v_mfma_f32_16x16x32_bf16 v[80:83], v[156:159], v[212:215], v[80:83]
	v_mfma_f32_16x16x32_bf16 v[72:75], v[164:167], v[212:215], v[72:75]
	v_mfma_f32_16x16x32_bf16 v[124:127], v[160:163], v[192:195], v[124:127]
	v_mfma_f32_16x16x32_bf16 v[120:123], v[168:171], v[192:195], v[120:123]
	v_mfma_f32_16x16x32_bf16 v[112:115], v[160:163], v[200:203], v[112:115]
	v_mfma_f32_16x16x32_bf16 v[104:107], v[168:171], v[200:203], v[104:107]
	v_mfma_f32_16x16x32_bf16 v[96:99], v[160:163], v[208:211], v[96:99]
	v_mfma_f32_16x16x32_bf16 v[88:91], v[168:171], v[208:211], v[88:91]
	v_mfma_f32_16x16x32_bf16 v[80:83], v[160:163], v[216:219], v[80:83]
	v_mfma_f32_16x16x32_bf16 v[72:75], v[168:171], v[216:219], v[72:75]
	s_setprio 0
	s_setprio 1
	v_mfma_f32_16x16x32_bf16 v[116:119], v[172:175], v[188:191], v[116:119]
	v_mfma_f32_16x16x32_bf16 v[108:111], v[180:183], v[188:191], v[108:111]
	v_mfma_f32_16x16x32_bf16 v[100:103], v[172:175], v[196:199], v[100:103]
	v_mfma_f32_16x16x32_bf16 v[92:95], v[180:183], v[196:199], v[92:95]
	v_mfma_f32_16x16x32_bf16 v[84:87], v[172:175], v[204:207], v[84:87]
	v_mfma_f32_16x16x32_bf16 v[76:79], v[180:183], v[204:207], v[76:79]
	v_mfma_f32_16x16x32_bf16 v[68:71], v[172:175], v[212:215], v[68:71]
	v_mfma_f32_16x16x32_bf16 v[64:67], v[180:183], v[212:215], v[64:67]
	v_mfma_f32_16x16x32_bf16 v[116:119], v[176:179], v[192:195], v[116:119]
	v_mfma_f32_16x16x32_bf16 v[108:111], v[184:187], v[192:195], v[108:111]
	v_mfma_f32_16x16x32_bf16 v[100:103], v[176:179], v[200:203], v[100:103]
	v_mfma_f32_16x16x32_bf16 v[92:95], v[184:187], v[200:203], v[92:95]
	v_mfma_f32_16x16x32_bf16 v[84:87], v[176:179], v[208:211], v[84:87]
	v_mfma_f32_16x16x32_bf16 v[76:79], v[184:187], v[208:211], v[76:79]
	v_mfma_f32_16x16x32_bf16 v[68:71], v[176:179], v[216:219], v[68:71]
	v_mfma_f32_16x16x32_bf16 v[64:67], v[184:187], v[216:219], v[64:67]
	s_setprio 0
	s_barrier
	s_add_i32 s65, s58, s24
	v_lshl_add_u64 v[148:149], s[40:41], 0, v[132:133]
	s_mov_b32 m0, s65
	ds_read_b128 v[188:191], v154 offset:16384
	ds_read_b128 v[192:195], v154 offset:17408
	ds_read_b128 v[196:199], v154 offset:18432
	ds_read_b128 v[200:203], v154 offset:19456
	ds_read_b128 v[204:207], v154 offset:20480
	ds_read_b128 v[208:211], v154 offset:21504
	ds_read_b128 v[212:215], v154 offset:22528
	ds_read_b128 v[216:219], v154 offset:23552
	global_load_lds_dwordx4 v[148:149], off
	s_add_i32 m0, s65, 0x2000
	s_add_u32 s66, s40, 0x100000
	v_lshl_add_u64 v[220:221], s[40:41], 0, v[128:129]
	s_addc_u32 s67, s41, 0
	s_add_i32 s65, s59, s24
	global_load_lds_dwordx4 v[220:221], off
	v_lshl_add_u64 v[222:223], s[66:67], 0, v[132:133]
	s_mov_b32 m0, s65
	v_lshl_add_u64 v[224:225], s[56:57], 0, v[130:131]
	global_load_lds_dwordx4 v[222:223], off
	v_lshl_add_u64 v[222:223], s[66:67], 0, v[128:129]
	s_add_i32 m0, s65, 0x2000
	s_nop 0
	global_load_lds_dwordx4 v[222:223], off
	v_lshl_add_u64 v[222:223], s[56:57], 0, v[134:135]
	s_mov_b32 m0, s29
	s_nop 0
	global_load_lds_dwordx4 v[222:223], off
	s_mov_b32 m0, s30
	s_nop 0
	global_load_lds_dwordx4 v[224:225], off
	s_nop 0
	s_waitcnt vmcnt(8)
	s_waitcnt lgkmcnt(0)
	s_barrier
	s_setprio 1
	s_waitcnt lgkmcnt(0)
	v_mfma_f32_16x16x32_bf16 v[60:63], v[156:159], v[188:191], v[60:63]
	v_mfma_f32_16x16x32_bf16 v[56:59], v[164:167], v[188:191], v[56:59]
	v_mfma_f32_16x16x32_bf16 v[52:55], v[156:159], v[196:199], v[52:55]
	v_mfma_f32_16x16x32_bf16 v[44:47], v[164:167], v[196:199], v[44:47]
	v_mfma_f32_16x16x32_bf16 v[36:39], v[156:159], v[204:207], v[36:39]
	v_mfma_f32_16x16x32_bf16 v[28:31], v[164:167], v[204:207], v[28:31]
	v_mfma_f32_16x16x32_bf16 v[20:23], v[156:159], v[212:215], v[20:23]
	v_mfma_f32_16x16x32_bf16 v[12:15], v[164:167], v[212:215], v[12:15]
	v_mfma_f32_16x16x32_bf16 v[60:63], v[160:163], v[192:195], v[60:63]
	v_mfma_f32_16x16x32_bf16 v[56:59], v[168:171], v[192:195], v[56:59]
	v_mfma_f32_16x16x32_bf16 v[52:55], v[160:163], v[200:203], v[52:55]
	v_mfma_f32_16x16x32_bf16 v[44:47], v[168:171], v[200:203], v[44:47]
	v_mfma_f32_16x16x32_bf16 v[36:39], v[160:163], v[208:211], v[36:39]
	v_mfma_f32_16x16x32_bf16 v[28:31], v[168:171], v[208:211], v[28:31]
	v_mfma_f32_16x16x32_bf16 v[20:23], v[160:163], v[216:219], v[20:23]
	v_mfma_f32_16x16x32_bf16 v[12:15], v[168:171], v[216:219], v[12:15]
	s_setprio 0
	s_setprio 1
	v_mfma_f32_16x16x32_bf16 v[48:51], v[172:175], v[188:191], v[48:51]
	v_mfma_f32_16x16x32_bf16 v[40:43], v[180:183], v[188:191], v[40:43]
	v_mfma_f32_16x16x32_bf16 v[32:35], v[172:175], v[196:199], v[32:35]
	v_mfma_f32_16x16x32_bf16 v[24:27], v[180:183], v[196:199], v[24:27]
	v_mfma_f32_16x16x32_bf16 v[16:19], v[172:175], v[204:207], v[16:19]
	v_mfma_f32_16x16x32_bf16 v[8:11], v[180:183], v[204:207], v[8:11]
	v_mfma_f32_16x16x32_bf16 v[4:7], v[172:175], v[212:215], v[4:7]
	v_mfma_f32_16x16x32_bf16 v[0:3], v[180:183], v[212:215], v[0:3]
	v_mfma_f32_16x16x32_bf16 v[48:51], v[176:179], v[192:195], v[48:51]
	v_mfma_f32_16x16x32_bf16 v[40:43], v[184:187], v[192:195], v[40:43]
	v_mfma_f32_16x16x32_bf16 v[32:35], v[176:179], v[200:203], v[32:35]
	v_mfma_f32_16x16x32_bf16 v[24:27], v[184:187], v[200:203], v[24:27]
	v_mfma_f32_16x16x32_bf16 v[16:19], v[176:179], v[208:211], v[16:19]
	v_mfma_f32_16x16x32_bf16 v[8:11], v[184:187], v[208:211], v[8:11]
	v_mfma_f32_16x16x32_bf16 v[4:7], v[176:179], v[216:219], v[4:7]
	v_mfma_f32_16x16x32_bf16 v[0:3], v[184:187], v[216:219], v[0:3]
	s_setprio 0
	s_barrier
	s_add_i32 s65, 0, 0x18000
	v_add_u32_e32 v155, s65, v151
	s_add_i32 s66, 0, 0x1c000
	ds_read_b128 v[156:159], v155
	ds_read_b128 v[160:163], v155 offset:1024
	ds_read_b128 v[164:167], v155 offset:2048
	ds_read_b128 v[168:171], v155 offset:3072
	v_add_u32_e32 v155, s66, v151
	ds_read_b128 v[172:175], v155
	ds_read_b128 v[176:179], v155 offset:1024
	ds_read_b128 v[180:183], v155 offset:2048
	ds_read_b128 v[184:187], v155 offset:3072
	s_add_u32 s56, s56, 0x100000
	s_addc_u32 s57, s57, 0
	s_mov_b32 m0, s31
	v_lshl_add_u64 v[226:227], s[56:57], 0, v[134:135]
	ds_read_b128 v[188:191], v154 offset:32768
	ds_read_b128 v[192:195], v154 offset:33792
	ds_read_b128 v[196:199], v154 offset:34816
	ds_read_b128 v[200:203], v154 offset:35840
	ds_read_b128 v[204:207], v154 offset:36864
	ds_read_b128 v[208:211], v154 offset:37888
	ds_read_b128 v[212:215], v154 offset:38912
	ds_read_b128 v[216:219], v154 offset:39936
	global_load_lds_dwordx4 v[226:227], off
	v_lshl_add_u64 v[226:227], s[56:57], 0, v[130:131]
	s_mov_b32 m0, s33
	s_nop 0
	global_load_lds_dwordx4 v[226:227], off
	s_nop 0
	s_waitcnt vmcnt(8)
	s_waitcnt lgkmcnt(0)
	s_barrier
	s_setprio 1
	s_waitcnt lgkmcnt(0)
	v_mfma_f32_16x16x32_bf16 v[124:127], v[156:159], v[188:191], v[124:127]
	v_mfma_f32_16x16x32_bf16 v[120:123], v[164:167], v[188:191], v[120:123]
	v_mfma_f32_16x16x32_bf16 v[112:115], v[156:159], v[196:199], v[112:115]
	v_mfma_f32_16x16x32_bf16 v[104:107], v[164:167], v[196:199], v[104:107]
	v_mfma_f32_16x16x32_bf16 v[96:99], v[156:159], v[204:207], v[96:99]
	v_mfma_f32_16x16x32_bf16 v[88:91], v[164:167], v[204:207], v[88:91]
	v_mfma_f32_16x16x32_bf16 v[80:83], v[156:159], v[212:215], v[80:83]
	v_mfma_f32_16x16x32_bf16 v[72:75], v[164:167], v[212:215], v[72:75]
	v_mfma_f32_16x16x32_bf16 v[124:127], v[160:163], v[192:195], v[124:127]
	v_mfma_f32_16x16x32_bf16 v[120:123], v[168:171], v[192:195], v[120:123]
	v_mfma_f32_16x16x32_bf16 v[112:115], v[160:163], v[200:203], v[112:115]
	v_mfma_f32_16x16x32_bf16 v[104:107], v[168:171], v[200:203], v[104:107]
	v_mfma_f32_16x16x32_bf16 v[96:99], v[160:163], v[208:211], v[96:99]
	v_mfma_f32_16x16x32_bf16 v[88:91], v[168:171], v[208:211], v[88:91]
	v_mfma_f32_16x16x32_bf16 v[80:83], v[160:163], v[216:219], v[80:83]
	v_mfma_f32_16x16x32_bf16 v[72:75], v[168:171], v[216:219], v[72:75]
	s_setprio 0
	s_setprio 1
	v_mfma_f32_16x16x32_bf16 v[116:119], v[172:175], v[188:191], v[116:119]
	v_mfma_f32_16x16x32_bf16 v[108:111], v[180:183], v[188:191], v[108:111]
	v_mfma_f32_16x16x32_bf16 v[100:103], v[172:175], v[196:199], v[100:103]
	v_mfma_f32_16x16x32_bf16 v[92:95], v[180:183], v[196:199], v[92:95]
	v_mfma_f32_16x16x32_bf16 v[84:87], v[172:175], v[204:207], v[84:87]
	v_mfma_f32_16x16x32_bf16 v[76:79], v[180:183], v[204:207], v[76:79]
	v_mfma_f32_16x16x32_bf16 v[68:71], v[172:175], v[212:215], v[68:71]
	v_mfma_f32_16x16x32_bf16 v[64:67], v[180:183], v[212:215], v[64:67]
	v_mfma_f32_16x16x32_bf16 v[116:119], v[176:179], v[192:195], v[116:119]
	v_mfma_f32_16x16x32_bf16 v[108:111], v[184:187], v[192:195], v[108:111]
	v_mfma_f32_16x16x32_bf16 v[100:103], v[176:179], v[200:203], v[100:103]
	v_mfma_f32_16x16x32_bf16 v[92:95], v[184:187], v[200:203], v[92:95]
	v_mfma_f32_16x16x32_bf16 v[84:87], v[176:179], v[208:211], v[84:87]
	v_mfma_f32_16x16x32_bf16 v[76:79], v[184:187], v[208:211], v[76:79]
	v_mfma_f32_16x16x32_bf16 v[68:71], v[176:179], v[216:219], v[68:71]
	v_mfma_f32_16x16x32_bf16 v[64:67], v[184:187], v[216:219], v[64:67]
	s_setprio 0
	s_barrier
	s_add_i32 s56, s65, s24
	v_lshl_add_u64 v[148:149], v[148:149], 0, s[10:11]
	s_mov_b32 m0, s56
	ds_read_b128 v[188:191], v154 offset:49152
	ds_read_b128 v[192:195], v154 offset:50176
	ds_read_b128 v[196:199], v154 offset:51200
	ds_read_b128 v[200:203], v154 offset:52224
	ds_read_b128 v[204:207], v154 offset:53248
	ds_read_b128 v[208:211], v154 offset:54272
	ds_read_b128 v[212:215], v154 offset:55296
	ds_read_b128 v[216:219], v154 offset:56320
	global_load_lds_dwordx4 v[148:149], off
	s_add_i32 m0, s56, 0x2000
	s_add_u32 s40, s40, 0x100080
	v_lshl_add_u64 v[148:149], v[220:221], 0, s[10:11]
	s_addc_u32 s41, s41, 0
	s_add_i32 s56, s66, s24
	global_load_lds_dwordx4 v[148:149], off
	v_lshl_add_u64 v[148:149], s[40:41], 0, v[132:133]
	s_mov_b32 m0, s56
	s_nop 0
	global_load_lds_dwordx4 v[148:149], off
	v_lshl_add_u64 v[148:149], s[40:41], 0, v[128:129]
	s_add_i32 m0, s56, 0x2000
	s_nop 0
	global_load_lds_dwordx4 v[148:149], off
	v_lshl_add_u64 v[148:149], v[222:223], 0, s[10:11]
	s_mov_b32 m0, s54
	s_nop 0
	global_load_lds_dwordx4 v[148:149], off
	v_lshl_add_u64 v[148:149], v[224:225], 0, s[10:11]
	s_mov_b32 m0, s55
	s_nop 0
	global_load_lds_dwordx4 v[148:149], off
	s_waitcnt vmcnt(8)
	s_waitcnt lgkmcnt(0)
	s_barrier
	s_setprio 1
	s_waitcnt lgkmcnt(0)
	v_mfma_f32_16x16x32_bf16 v[60:63], v[156:159], v[188:191], v[60:63]
	v_mfma_f32_16x16x32_bf16 v[56:59], v[164:167], v[188:191], v[56:59]
	v_mfma_f32_16x16x32_bf16 v[52:55], v[156:159], v[196:199], v[52:55]
	v_mfma_f32_16x16x32_bf16 v[44:47], v[164:167], v[196:199], v[44:47]
	v_mfma_f32_16x16x32_bf16 v[36:39], v[156:159], v[204:207], v[36:39]
	v_mfma_f32_16x16x32_bf16 v[28:31], v[164:167], v[204:207], v[28:31]
	v_mfma_f32_16x16x32_bf16 v[20:23], v[156:159], v[212:215], v[20:23]
	v_mfma_f32_16x16x32_bf16 v[12:15], v[164:167], v[212:215], v[12:15]
	v_mfma_f32_16x16x32_bf16 v[60:63], v[160:163], v[192:195], v[60:63]
	v_mfma_f32_16x16x32_bf16 v[56:59], v[168:171], v[192:195], v[56:59]
	v_mfma_f32_16x16x32_bf16 v[52:55], v[160:163], v[200:203], v[52:55]
	v_mfma_f32_16x16x32_bf16 v[44:47], v[168:171], v[200:203], v[44:47]
	v_mfma_f32_16x16x32_bf16 v[36:39], v[160:163], v[208:211], v[36:39]
	v_mfma_f32_16x16x32_bf16 v[28:31], v[168:171], v[208:211], v[28:31]
	v_mfma_f32_16x16x32_bf16 v[20:23], v[160:163], v[216:219], v[20:23]
	v_mfma_f32_16x16x32_bf16 v[12:15], v[168:171], v[216:219], v[12:15]
	s_setprio 0
	s_setprio 1
	v_mfma_f32_16x16x32_bf16 v[48:51], v[172:175], v[188:191], v[48:51]
	v_mfma_f32_16x16x32_bf16 v[40:43], v[180:183], v[188:191], v[40:43]
	v_mfma_f32_16x16x32_bf16 v[32:35], v[172:175], v[196:199], v[32:35]
	v_mfma_f32_16x16x32_bf16 v[24:27], v[180:183], v[196:199], v[24:27]
	v_mfma_f32_16x16x32_bf16 v[16:19], v[172:175], v[204:207], v[16:19]
	v_mfma_f32_16x16x32_bf16 v[8:11], v[180:183], v[204:207], v[8:11]
	v_mfma_f32_16x16x32_bf16 v[4:7], v[172:175], v[212:215], v[4:7]
	v_mfma_f32_16x16x32_bf16 v[0:3], v[180:183], v[212:215], v[0:3]
	v_mfma_f32_16x16x32_bf16 v[48:51], v[176:179], v[192:195], v[48:51]
	v_mfma_f32_16x16x32_bf16 v[40:43], v[184:187], v[192:195], v[40:43]
	v_mfma_f32_16x16x32_bf16 v[32:35], v[176:179], v[200:203], v[32:35]
	v_mfma_f32_16x16x32_bf16 v[24:27], v[184:187], v[200:203], v[24:27]
	v_mfma_f32_16x16x32_bf16 v[16:19], v[176:179], v[208:211], v[16:19]
	v_mfma_f32_16x16x32_bf16 v[8:11], v[184:187], v[208:211], v[8:11]
	v_mfma_f32_16x16x32_bf16 v[4:7], v[176:179], v[216:219], v[4:7]
	v_mfma_f32_16x16x32_bf16 v[0:3], v[184:187], v[216:219], v[0:3]
	s_setprio 0
	s_barrier
	s_add_i32 s64, s64, 2
	s_add_u32 s38, s38, 0x100
	s_addc_u32 s39, s39, 0
	s_add_u32 s62, s62, 0x100
	s_addc_u32 s63, s63, 0
	s_cmp_gt_u32 s64, 61
	s_cbranch_scc0 .LBB0_394
	s_and_b64 vcc, exec, s[12:13]
	s_cbranch_vccz .LBB0_397
	s_barrier

.LBB0_622:
	ds_read_b128 v[152:155], v149
	ds_read_b128 v[156:159], v149 offset:1024
	ds_read_b128 v[160:163], v149 offset:2048
	ds_read_b128 v[164:167], v149 offset:3072
	ds_read_b128 v[168:171], v150
	ds_read_b128 v[172:175], v150 offset:1024
	ds_read_b128 v[176:179], v150 offset:2048
	ds_read_b128 v[180:183], v150 offset:3072
	s_add_u32 s42, s40, 0xfff00080
	s_addc_u32 s43, s41, -1
	s_cmp_eq_u32 s61, 60
	s_cselect_b32 s45, s25, s43
	s_cselect_b32 s44, s57, s42
	s_cselect_b32 s43, s23, s60
	s_cselect_b32 s42, s58, s59
	v_lshl_add_u64 v[144:145], s[40:41], 0, v[136:137]
	s_add_i32 m0, s31, 0xc000
	ds_read_b128 v[184:187], v151
	ds_read_b128 v[188:191], v151 offset:1024
	ds_read_b128 v[192:195], v151 offset:2048
	ds_read_b128 v[196:199], v151 offset:3072
	ds_read_b128 v[200:203], v151 offset:4096
	ds_read_b128 v[204:207], v151 offset:5120
	ds_read_b128 v[208:211], v151 offset:6144
	ds_read_b128 v[212:215], v151 offset:7168
	global_load_lds_dwordx4 v[144:145], off
	v_lshl_add_u64 v[144:145], s[40:41], 0, v[138:139]
	s_add_i32 m0, s31, 0xe000
	s_nop 0
	global_load_lds_dwordx4 v[144:145], off
	s_waitcnt vmcnt(8)
	s_waitcnt lgkmcnt(0)
	s_barrier
	s_setprio 1
	s_waitcnt lgkmcnt(0)
	v_mfma_f32_16x16x32_bf16 v[124:127], v[152:155], v[184:187], v[124:127]
	v_mfma_f32_16x16x32_bf16 v[120:123], v[160:163], v[184:187], v[120:123]
	v_mfma_f32_16x16x32_bf16 v[116:119], v[152:155], v[192:195], v[116:119]
	v_mfma_f32_16x16x32_bf16 v[108:111], v[160:163], v[192:195], v[108:111]
	v_mfma_f32_16x16x32_bf16 v[100:103], v[152:155], v[200:203], v[100:103]
	v_mfma_f32_16x16x32_bf16 v[92:95], v[160:163], v[200:203], v[92:95]
	v_mfma_f32_16x16x32_bf16 v[84:87], v[152:155], v[208:211], v[84:87]
	v_mfma_f32_16x16x32_bf16 v[76:79], v[160:163], v[208:211], v[76:79]
	v_mfma_f32_16x16x32_bf16 v[124:127], v[156:159], v[188:191], v[124:127]
	v_mfma_f32_16x16x32_bf16 v[120:123], v[164:167], v[188:191], v[120:123]
	v_mfma_f32_16x16x32_bf16 v[116:119], v[156:159], v[196:199], v[116:119]
	v_mfma_f32_16x16x32_bf16 v[108:111], v[164:167], v[196:199], v[108:111]
	v_mfma_f32_16x16x32_bf16 v[100:103], v[156:159], v[204:207], v[100:103]
	v_mfma_f32_16x16x32_bf16 v[92:95], v[164:167], v[204:207], v[92:95]
	v_mfma_f32_16x16x32_bf16 v[84:87], v[156:159], v[212:215], v[84:87]
	v_mfma_f32_16x16x32_bf16 v[76:79], v[164:167], v[212:215], v[76:79]
	s_setprio 0
	s_setprio 1
	v_mfma_f32_16x16x32_bf16 v[112:115], v[168:171], v[184:187], v[112:115]
	v_mfma_f32_16x16x32_bf16 v[104:107], v[176:179], v[184:187], v[104:107]
	v_mfma_f32_16x16x32_bf16 v[96:99], v[168:171], v[192:195], v[96:99]
	v_mfma_f32_16x16x32_bf16 v[88:91], v[176:179], v[192:195], v[88:91]
	v_mfma_f32_16x16x32_bf16 v[80:83], v[168:171], v[200:203], v[80:83]
	v_mfma_f32_16x16x32_bf16 v[72:75], v[176:179], v[200:203], v[72:75]
	v_mfma_f32_16x16x32_bf16 v[68:71], v[168:171], v[208:211], v[68:71]
	v_mfma_f32_16x16x32_bf16 v[64:67], v[176:179], v[208:211], v[64:67]
	v_mfma_f32_16x16x32_bf16 v[112:115], v[172:175], v[188:191], v[112:115]
	v_mfma_f32_16x16x32_bf16 v[104:107], v[180:183], v[188:191], v[104:107]
	v_mfma_f32_16x16x32_bf16 v[96:99], v[172:175], v[196:199], v[96:99]
	v_mfma_f32_16x16x32_bf16 v[88:91], v[180:183], v[196:199], v[88:91]
	v_mfma_f32_16x16x32_bf16 v[80:83], v[172:175], v[204:207], v[80:83]
	v_mfma_f32_16x16x32_bf16 v[72:75], v[180:183], v[204:207], v[72:75]
	v_mfma_f32_16x16x32_bf16 v[68:71], v[172:175], v[212:215], v[68:71]
	v_mfma_f32_16x16x32_bf16 v[64:67], v[180:183], v[212:215], v[64:67]
	s_setprio 0
	s_barrier
	s_add_i32 s62, s50, s29
	v_lshl_add_u64 v[144:145], s[42:43], 0, v[132:133]
	s_mov_b32 m0, s62
	ds_read_b128 v[184:187], v151 offset:16384
	ds_read_b128 v[188:191], v151 offset:17408
	ds_read_b128 v[192:195], v151 offset:18432
	ds_read_b128 v[196:199], v151 offset:19456
	ds_read_b128 v[200:203], v151 offset:20480
	ds_read_b128 v[204:207], v151 offset:21504
	ds_read_b128 v[208:211], v151 offset:22528
	ds_read_b128 v[212:215], v151 offset:23552
	global_load_lds_dwordx4 v[144:145], off
	s_add_i32 m0, s62, 0x2000
	s_add_u32 s62, s42, 0x100000
	v_lshl_add_u64 v[216:217], s[42:43], 0, v[128:129]
	s_addc_u32 s63, s43, 0
	s_add_i32 s64, s51, s29
	global_load_lds_dwordx4 v[216:217], off
	v_lshl_add_u64 v[218:219], s[62:63], 0, v[132:133]
	s_mov_b32 m0, s64
	v_lshl_add_u64 v[220:221], s[44:45], 0, v[130:131]
	global_load_lds_dwordx4 v[218:219], off
	v_lshl_add_u64 v[218:219], s[62:63], 0, v[128:129]
	s_add_i32 m0, s64, 0x2000
	s_nop 0
	global_load_lds_dwordx4 v[218:219], off
	v_lshl_add_u64 v[218:219], s[44:45], 0, v[134:135]
	s_mov_b32 m0, s31
	s_nop 0
	global_load_lds_dwordx4 v[218:219], off
	s_mov_b32 m0, s33
	s_nop 0
	global_load_lds_dwordx4 v[220:221], off
	s_nop 0
	s_waitcnt vmcnt(8)
	s_waitcnt lgkmcnt(0)
	s_barrier
	s_setprio 1
	s_waitcnt lgkmcnt(0)
	v_mfma_f32_16x16x32_bf16 v[60:63], v[152:155], v[184:187], v[60:63]
	v_mfma_f32_16x16x32_bf16 v[56:59], v[160:163], v[184:187], v[56:59]
	v_mfma_f32_16x16x32_bf16 v[52:55], v[152:155], v[192:195], v[52:55]
	v_mfma_f32_16x16x32_bf16 v[44:47], v[160:163], v[192:195], v[44:47]
	v_mfma_f32_16x16x32_bf16 v[36:39], v[152:155], v[200:203], v[36:39]
	v_mfma_f32_16x16x32_bf16 v[28:31], v[160:163], v[200:203], v[28:31]
	v_mfma_f32_16x16x32_bf16 v[20:23], v[152:155], v[208:211], v[20:23]
	v_mfma_f32_16x16x32_bf16 v[12:15], v[160:163], v[208:211], v[12:15]
	v_mfma_f32_16x16x32_bf16 v[60:63], v[156:159], v[188:191], v[60:63]
	v_mfma_f32_16x16x32_bf16 v[56:59], v[164:167], v[188:191], v[56:59]
	v_mfma_f32_16x16x32_bf16 v[52:55], v[156:159], v[196:199], v[52:55]
	v_mfma_f32_16x16x32_bf16 v[44:47], v[164:167], v[196:199], v[44:47]
	v_mfma_f32_16x16x32_bf16 v[36:39], v[156:159], v[204:207], v[36:39]
	v_mfma_f32_16x16x32_bf16 v[28:31], v[164:167], v[204:207], v[28:31]
	v_mfma_f32_16x16x32_bf16 v[20:23], v[156:159], v[212:215], v[20:23]
	v_mfma_f32_16x16x32_bf16 v[12:15], v[164:167], v[212:215], v[12:15]
	s_setprio 0
	s_setprio 1
	v_mfma_f32_16x16x32_bf16 v[48:51], v[168:171], v[184:187], v[48:51]
	v_mfma_f32_16x16x32_bf16 v[40:43], v[176:179], v[184:187], v[40:43]
	v_mfma_f32_16x16x32_bf16 v[32:35], v[168:171], v[192:195], v[32:35]
	v_mfma_f32_16x16x32_bf16 v[24:27], v[176:179], v[192:195], v[24:27]
	v_mfma_f32_16x16x32_bf16 v[16:19], v[168:171], v[200:203], v[16:19]
	v_mfma_f32_16x16x32_bf16 v[8:11], v[176:179], v[200:203], v[8:11]
	v_mfma_f32_16x16x32_bf16 v[4:7], v[168:171], v[208:211], v[4:7]
	v_mfma_f32_16x16x32_bf16 v[0:3], v[176:179], v[208:211], v[0:3]
	v_mfma_f32_16x16x32_bf16 v[48:51], v[172:175], v[188:191], v[48:51]
	v_mfma_f32_16x16x32_bf16 v[40:43], v[180:183], v[188:191], v[40:43]
	v_mfma_f32_16x16x32_bf16 v[32:35], v[172:175], v[196:199], v[32:35]
	v_mfma_f32_16x16x32_bf16 v[24:27], v[180:183], v[196:199], v[24:27]
	v_mfma_f32_16x16x32_bf16 v[16:19], v[172:175], v[204:207], v[16:19]
	v_mfma_f32_16x16x32_bf16 v[8:11], v[180:183], v[204:207], v[8:11]
	v_mfma_f32_16x16x32_bf16 v[4:7], v[172:175], v[212:215], v[4:7]
	v_mfma_f32_16x16x32_bf16 v[0:3], v[180:183], v[212:215], v[0:3]
	s_setprio 0
	s_barrier
	s_add_i32 s62, 0, 0x18000
	s_add_i32 s63, 0, 0x1c000
	v_add_u32_e32 v164, s62, v147
	v_add_u32_e32 v180, s63, v147
	ds_read_b128 v[152:155], v164
	ds_read_b128 v[156:159], v164 offset:1024
	ds_read_b128 v[160:163], v164 offset:2048
	ds_read_b128 v[164:167], v164 offset:3072
	ds_read_b128 v[168:171], v180
	ds_read_b128 v[172:175], v180 offset:1024
	ds_read_b128 v[176:179], v180 offset:2048
	ds_read_b128 v[180:183], v180 offset:3072
	s_add_u32 s44, s44, 0x100000
	s_addc_u32 s45, s45, 0
	s_mov_b32 m0, s35
	v_lshl_add_u64 v[222:223], s[44:45], 0, v[134:135]
	ds_read_b128 v[184:187], v151 offset:32768
	ds_read_b128 v[188:191], v151 offset:33792
	ds_read_b128 v[192:195], v151 offset:34816
	ds_read_b128 v[196:199], v151 offset:35840
	ds_read_b128 v[200:203], v151 offset:36864
	ds_read_b128 v[204:207], v151 offset:37888
	ds_read_b128 v[208:211], v151 offset:38912
	ds_read_b128 v[212:215], v151 offset:39936
	global_load_lds_dwordx4 v[222:223], off
	v_lshl_add_u64 v[222:223], s[44:45], 0, v[130:131]
	s_mov_b32 m0, s39
	s_nop 0
	global_load_lds_dwordx4 v[222:223], off
	s_nop 0
	s_waitcnt vmcnt(8)
	s_waitcnt lgkmcnt(0)
	s_barrier
	s_setprio 1
	s_waitcnt lgkmcnt(0)
	v_mfma_f32_16x16x32_bf16 v[124:127], v[152:155], v[184:187], v[124:127]
	v_mfma_f32_16x16x32_bf16 v[120:123], v[160:163], v[184:187], v[120:123]
	v_mfma_f32_16x16x32_bf16 v[116:119], v[152:155], v[192:195], v[116:119]
	v_mfma_f32_16x16x32_bf16 v[108:111], v[160:163], v[192:195], v[108:111]
	v_mfma_f32_16x16x32_bf16 v[100:103], v[152:155], v[200:203], v[100:103]
	v_mfma_f32_16x16x32_bf16 v[92:95], v[160:163], v[200:203], v[92:95]
	v_mfma_f32_16x16x32_bf16 v[84:87], v[152:155], v[208:211], v[84:87]
	v_mfma_f32_16x16x32_bf16 v[76:79], v[160:163], v[208:211], v[76:79]
	v_mfma_f32_16x16x32_bf16 v[124:127], v[156:159], v[188:191], v[124:127]
	v_mfma_f32_16x16x32_bf16 v[120:123], v[164:167], v[188:191], v[120:123]
	v_mfma_f32_16x16x32_bf16 v[116:119], v[156:159], v[196:199], v[116:119]
	v_mfma_f32_16x16x32_bf16 v[108:111], v[164:167], v[196:199], v[108:111]
	v_mfma_f32_16x16x32_bf16 v[100:103], v[156:159], v[204:207], v[100:103]
	v_mfma_f32_16x16x32_bf16 v[92:95], v[164:167], v[204:207], v[92:95]
	v_mfma_f32_16x16x32_bf16 v[84:87], v[156:159], v[212:215], v[84:87]
	v_mfma_f32_16x16x32_bf16 v[76:79], v[164:167], v[212:215], v[76:79]
	s_setprio 0
	s_setprio 1
	v_mfma_f32_16x16x32_bf16 v[112:115], v[168:171], v[184:187], v[112:115]
	v_mfma_f32_16x16x32_bf16 v[104:107], v[176:179], v[184:187], v[104:107]
	v_mfma_f32_16x16x32_bf16 v[96:99], v[168:171], v[192:195], v[96:99]
	v_mfma_f32_16x16x32_bf16 v[88:91], v[176:179], v[192:195], v[88:91]
	v_mfma_f32_16x16x32_bf16 v[80:83], v[168:171], v[200:203], v[80:83]
	v_mfma_f32_16x16x32_bf16 v[72:75], v[176:179], v[200:203], v[72:75]
	v_mfma_f32_16x16x32_bf16 v[68:71], v[168:171], v[208:211], v[68:71]
	v_mfma_f32_16x16x32_bf16 v[64:67], v[176:179], v[208:211], v[64:67]
	v_mfma_f32_16x16x32_bf16 v[112:115], v[172:175], v[188:191], v[112:115]
	v_mfma_f32_16x16x32_bf16 v[104:107], v[180:183], v[188:191], v[104:107]
	v_mfma_f32_16x16x32_bf16 v[96:99], v[172:175], v[196:199], v[96:99]
	v_mfma_f32_16x16x32_bf16 v[88:91], v[180:183], v[196:199], v[88:91]
	v_mfma_f32_16x16x32_bf16 v[80:83], v[172:175], v[204:207], v[80:83]
	v_mfma_f32_16x16x32_bf16 v[72:75], v[180:183], v[204:207], v[72:75]
	v_mfma_f32_16x16x32_bf16 v[68:71], v[172:175], v[212:215], v[68:71]
	v_mfma_f32_16x16x32_bf16 v[64:67], v[180:183], v[212:215], v[64:67]
	s_setprio 0
	s_barrier
	s_add_i32 s44, s62, s29
	v_lshl_add_u64 v[144:145], v[144:145], 0, s[8:9]
	s_mov_b32 m0, s44
	ds_read_b128 v[184:187], v151 offset:49152
	ds_read_b128 v[188:191], v151 offset:50176
	ds_read_b128 v[192:195], v151 offset:51200
	ds_read_b128 v[196:199], v151 offset:52224
	ds_read_b128 v[200:203], v151 offset:53248
	ds_read_b128 v[204:207], v151 offset:54272
	ds_read_b128 v[208:211], v151 offset:55296
	ds_read_b128 v[212:215], v151 offset:56320
	global_load_lds_dwordx4 v[144:145], off
	s_add_i32 m0, s44, 0x2000
	s_add_u32 s42, s42, 0x100080
	v_lshl_add_u64 v[144:145], v[216:217], 0, s[8:9]
	s_addc_u32 s43, s43, 0
	s_add_i32 s44, s63, s29
	global_load_lds_dwordx4 v[144:145], off
	v_lshl_add_u64 v[144:145], s[42:43], 0, v[132:133]
	s_mov_b32 m0, s44
	s_nop 0
	global_load_lds_dwordx4 v[144:145], off
	v_lshl_add_u64 v[144:145], s[42:43], 0, v[128:129]
	s_add_i32 m0, s44, 0x2000
	s_nop 0
	global_load_lds_dwordx4 v[144:145], off
	v_lshl_add_u64 v[144:145], v[218:219], 0, s[8:9]
	s_mov_b32 m0, s48
	s_nop 0
	global_load_lds_dwordx4 v[144:145], off
	v_lshl_add_u64 v[144:145], v[220:221], 0, s[8:9]
	s_mov_b32 m0, s49
	s_nop 0
	global_load_lds_dwordx4 v[144:145], off
	s_waitcnt vmcnt(8)
	s_waitcnt lgkmcnt(0)
	s_barrier
	s_setprio 1
	s_waitcnt lgkmcnt(0)
	v_mfma_f32_16x16x32_bf16 v[60:63], v[152:155], v[184:187], v[60:63]
	v_mfma_f32_16x16x32_bf16 v[56:59], v[160:163], v[184:187], v[56:59]
	v_mfma_f32_16x16x32_bf16 v[52:55], v[152:155], v[192:195], v[52:55]
	v_mfma_f32_16x16x32_bf16 v[44:47], v[160:163], v[192:195], v[44:47]
	v_mfma_f32_16x16x32_bf16 v[36:39], v[152:155], v[200:203], v[36:39]
	v_mfma_f32_16x16x32_bf16 v[28:31], v[160:163], v[200:203], v[28:31]
	v_mfma_f32_16x16x32_bf16 v[20:23], v[152:155], v[208:211], v[20:23]
	v_mfma_f32_16x16x32_bf16 v[12:15], v[160:163], v[208:211], v[12:15]
	v_mfma_f32_16x16x32_bf16 v[60:63], v[156:159], v[188:191], v[60:63]
	v_mfma_f32_16x16x32_bf16 v[56:59], v[164:167], v[188:191], v[56:59]
	v_mfma_f32_16x16x32_bf16 v[52:55], v[156:159], v[196:199], v[52:55]
	v_mfma_f32_16x16x32_bf16 v[44:47], v[164:167], v[196:199], v[44:47]
	v_mfma_f32_16x16x32_bf16 v[36:39], v[156:159], v[204:207], v[36:39]
	v_mfma_f32_16x16x32_bf16 v[28:31], v[164:167], v[204:207], v[28:31]
	v_mfma_f32_16x16x32_bf16 v[20:23], v[156:159], v[212:215], v[20:23]
	v_mfma_f32_16x16x32_bf16 v[12:15], v[164:167], v[212:215], v[12:15]
	s_setprio 0
	s_setprio 1
	v_mfma_f32_16x16x32_bf16 v[48:51], v[168:171], v[184:187], v[48:51]
	v_mfma_f32_16x16x32_bf16 v[40:43], v[176:179], v[184:187], v[40:43]
	v_mfma_f32_16x16x32_bf16 v[32:35], v[168:171], v[192:195], v[32:35]
	v_mfma_f32_16x16x32_bf16 v[24:27], v[176:179], v[192:195], v[24:27]
	v_mfma_f32_16x16x32_bf16 v[16:19], v[168:171], v[200:203], v[16:19]
	v_mfma_f32_16x16x32_bf16 v[8:11], v[176:179], v[200:203], v[8:11]
	v_mfma_f32_16x16x32_bf16 v[4:7], v[168:171], v[208:211], v[4:7]
	v_mfma_f32_16x16x32_bf16 v[0:3], v[176:179], v[208:211], v[0:3]
	v_mfma_f32_16x16x32_bf16 v[48:51], v[172:175], v[188:191], v[48:51]
	v_mfma_f32_16x16x32_bf16 v[40:43], v[180:183], v[188:191], v[40:43]
	v_mfma_f32_16x16x32_bf16 v[32:35], v[172:175], v[196:199], v[32:35]
	v_mfma_f32_16x16x32_bf16 v[24:27], v[180:183], v[196:199], v[24:27]
	v_mfma_f32_16x16x32_bf16 v[16:19], v[172:175], v[204:207], v[16:19]
	v_mfma_f32_16x16x32_bf16 v[8:11], v[180:183], v[204:207], v[8:11]
	v_mfma_f32_16x16x32_bf16 v[4:7], v[172:175], v[212:215], v[4:7]
	v_mfma_f32_16x16x32_bf16 v[0:3], v[180:183], v[212:215], v[0:3]
	s_setprio 0
	s_barrier
	s_add_i32 s61, s61, 2
	s_add_u32 s40, s40, 0x100
	s_addc_u32 s41, s41, 0
	s_add_u32 s59, s59, 0x100
	s_addc_u32 s60, s60, 0
	s_cmp_gt_u32 s61, 61
	s_cbranch_scc0 .LBB0_622
	s_and_b64 vcc, exec, s[10:11]
	s_cbranch_vccz .LBB0_625
	s_barrier

.LBB0_773:
	ds_read_b128 v[144:147], v155
	ds_read_b128 v[148:151], v155 offset:1024
	ds_read_b128 v[158:161], v155 offset:2048
	ds_read_b128 v[162:165], v155 offset:3072
	ds_read_b128 v[166:169], v156
	ds_read_b128 v[170:173], v156 offset:1024
	ds_read_b128 v[174:177], v156 offset:2048
	ds_read_b128 v[178:181], v156 offset:3072
	s_add_u32 s36, s30, 0xfff80080
	s_addc_u32 s37, s31, -1
	s_cmp_eq_u32 s52, 28
	s_cselect_b32 s39, s23, s37
	s_cselect_b32 s38, s48, s36
	s_cselect_b32 s37, s21, s51
	s_cselect_b32 s36, s49, s50
	v_lshl_add_u64 v[214:215], s[30:31], 0, v[136:137]
	s_add_i32 m0, s17, 0xc000
	ds_read_b128 v[182:185], v157
	ds_read_b128 v[186:189], v157 offset:1024
	ds_read_b128 v[190:193], v157 offset:2048
	ds_read_b128 v[194:197], v157 offset:3072
	ds_read_b128 v[198:201], v157 offset:4096
	ds_read_b128 v[202:205], v157 offset:5120
	ds_read_b128 v[206:209], v157 offset:6144
	ds_read_b128 v[210:213], v157 offset:7168
	global_load_lds_dwordx4 v[214:215], off
	v_lshl_add_u64 v[214:215], s[30:31], 0, v[138:139]
	s_add_i32 m0, s17, 0xe000
	s_nop 0
	global_load_lds_dwordx4 v[214:215], off
	s_nop 0
	s_waitcnt vmcnt(8)
	s_waitcnt lgkmcnt(0)
	s_barrier
	s_setprio 1
	s_waitcnt lgkmcnt(0)
	v_mfma_i32_16x16x64_i8 v[124:127], v[144:147], v[182:185], v[124:127]
	v_mfma_i32_16x16x64_i8 v[116:119], v[158:161], v[182:185], v[116:119]
	v_mfma_i32_16x16x64_i8 v[108:111], v[144:147], v[190:193], v[108:111]
	v_mfma_i32_16x16x64_i8 v[100:103], v[158:161], v[190:193], v[100:103]
	v_mfma_i32_16x16x64_i8 v[92:95], v[144:147], v[198:201], v[92:95]
	v_mfma_i32_16x16x64_i8 v[84:87], v[158:161], v[198:201], v[84:87]
	v_mfma_i32_16x16x64_i8 v[76:79], v[144:147], v[206:209], v[76:79]
	v_mfma_i32_16x16x64_i8 v[68:71], v[158:161], v[206:209], v[68:71]
	v_mfma_i32_16x16x64_i8 v[124:127], v[148:151], v[186:189], v[124:127]
	v_mfma_i32_16x16x64_i8 v[116:119], v[162:165], v[186:189], v[116:119]
	v_mfma_i32_16x16x64_i8 v[108:111], v[148:151], v[194:197], v[108:111]
	v_mfma_i32_16x16x64_i8 v[100:103], v[162:165], v[194:197], v[100:103]
	v_mfma_i32_16x16x64_i8 v[92:95], v[148:151], v[202:205], v[92:95]
	v_mfma_i32_16x16x64_i8 v[84:87], v[162:165], v[202:205], v[84:87]
	v_mfma_i32_16x16x64_i8 v[76:79], v[148:151], v[210:213], v[76:79]
	v_mfma_i32_16x16x64_i8 v[68:71], v[162:165], v[210:213], v[68:71]
	s_setprio 0
	s_setprio 1
	v_mfma_i32_16x16x64_i8 v[120:123], v[166:169], v[182:185], v[120:123]
	v_mfma_i32_16x16x64_i8 v[112:115], v[174:177], v[182:185], v[112:115]
	v_mfma_i32_16x16x64_i8 v[104:107], v[166:169], v[190:193], v[104:107]
	v_mfma_i32_16x16x64_i8 v[96:99], v[174:177], v[190:193], v[96:99]
	v_mfma_i32_16x16x64_i8 v[88:91], v[166:169], v[198:201], v[88:91]
	v_mfma_i32_16x16x64_i8 v[80:83], v[174:177], v[198:201], v[80:83]
	v_mfma_i32_16x16x64_i8 v[72:75], v[166:169], v[206:209], v[72:75]
	v_mfma_i32_16x16x64_i8 v[64:67], v[174:177], v[206:209], v[64:67]
	v_mfma_i32_16x16x64_i8 v[120:123], v[170:173], v[186:189], v[120:123]
	v_mfma_i32_16x16x64_i8 v[112:115], v[178:181], v[186:189], v[112:115]
	v_mfma_i32_16x16x64_i8 v[104:107], v[170:173], v[194:197], v[104:107]
	v_mfma_i32_16x16x64_i8 v[96:99], v[178:181], v[194:197], v[96:99]
	v_mfma_i32_16x16x64_i8 v[88:91], v[170:173], v[202:205], v[88:91]
	v_mfma_i32_16x16x64_i8 v[80:83], v[178:181], v[202:205], v[80:83]
	v_mfma_i32_16x16x64_i8 v[72:75], v[170:173], v[210:213], v[72:75]
	v_mfma_i32_16x16x64_i8 v[64:67], v[178:181], v[210:213], v[64:67]
	s_setprio 0
	s_barrier
	s_add_i32 s53, s44, s2
	v_lshl_add_u64 v[214:215], s[36:37], 0, v[132:133]
	s_mov_b32 m0, s53
	ds_read_b128 v[182:185], v157 offset:16384
	ds_read_b128 v[186:189], v157 offset:17408
	ds_read_b128 v[190:193], v157 offset:18432
	ds_read_b128 v[194:197], v157 offset:19456
	ds_read_b128 v[198:201], v157 offset:20480
	ds_read_b128 v[202:205], v157 offset:21504
	ds_read_b128 v[206:209], v157 offset:22528
	ds_read_b128 v[210:213], v157 offset:23552
	global_load_lds_dwordx4 v[214:215], off
	s_add_i32 m0, s53, 0x2000
	s_add_u32 s54, s36, 0x80000
	v_lshl_add_u64 v[216:217], s[36:37], 0, v[128:129]
	s_addc_u32 s55, s37, 0
	s_add_i32 s53, s45, s2
	global_load_lds_dwordx4 v[216:217], off
	v_lshl_add_u64 v[218:219], s[54:55], 0, v[132:133]
	s_mov_b32 m0, s53
	v_lshl_add_u64 v[220:221], s[38:39], 0, v[130:131]
	global_load_lds_dwordx4 v[218:219], off
	v_lshl_add_u64 v[218:219], s[54:55], 0, v[128:129]
	s_add_i32 m0, s53, 0x2000
	s_nop 0
	global_load_lds_dwordx4 v[218:219], off
	v_lshl_add_u64 v[218:219], s[38:39], 0, v[134:135]
	s_mov_b32 m0, s17
	s_nop 0
	global_load_lds_dwordx4 v[218:219], off
	s_mov_b32 m0, s29
	s_nop 0
	global_load_lds_dwordx4 v[220:221], off
	s_nop 0
	s_waitcnt vmcnt(8)
	s_waitcnt lgkmcnt(0)
	s_barrier
	s_setprio 1
	s_waitcnt lgkmcnt(0)
	v_mfma_i32_16x16x64_i8 v[60:63], v[144:147], v[182:185], v[60:63]
	v_mfma_i32_16x16x64_i8 v[52:55], v[158:161], v[182:185], v[52:55]
	v_mfma_i32_16x16x64_i8 v[44:47], v[144:147], v[190:193], v[44:47]
	v_mfma_i32_16x16x64_i8 v[36:39], v[158:161], v[190:193], v[36:39]
	v_mfma_i32_16x16x64_i8 v[28:31], v[144:147], v[198:201], v[28:31]
	v_mfma_i32_16x16x64_i8 v[20:23], v[158:161], v[198:201], v[20:23]
	v_mfma_i32_16x16x64_i8 v[12:15], v[144:147], v[206:209], v[12:15]
	v_mfma_i32_16x16x64_i8 v[4:7], v[158:161], v[206:209], v[4:7]
	v_mfma_i32_16x16x64_i8 v[60:63], v[148:151], v[186:189], v[60:63]
	v_mfma_i32_16x16x64_i8 v[52:55], v[162:165], v[186:189], v[52:55]
	v_mfma_i32_16x16x64_i8 v[44:47], v[148:151], v[194:197], v[44:47]
	v_mfma_i32_16x16x64_i8 v[36:39], v[162:165], v[194:197], v[36:39]
	v_mfma_i32_16x16x64_i8 v[28:31], v[148:151], v[202:205], v[28:31]
	v_mfma_i32_16x16x64_i8 v[20:23], v[162:165], v[202:205], v[20:23]
	v_mfma_i32_16x16x64_i8 v[12:15], v[148:151], v[210:213], v[12:15]
	v_mfma_i32_16x16x64_i8 v[4:7], v[162:165], v[210:213], v[4:7]
	s_setprio 0
	s_setprio 1
	v_mfma_i32_16x16x64_i8 v[56:59], v[166:169], v[182:185], v[56:59]
	v_mfma_i32_16x16x64_i8 v[48:51], v[174:177], v[182:185], v[48:51]
	v_mfma_i32_16x16x64_i8 v[40:43], v[166:169], v[190:193], v[40:43]
	v_mfma_i32_16x16x64_i8 v[32:35], v[174:177], v[190:193], v[32:35]
	v_mfma_i32_16x16x64_i8 v[24:27], v[166:169], v[198:201], v[24:27]
	v_mfma_i32_16x16x64_i8 v[16:19], v[174:177], v[198:201], v[16:19]
	v_mfma_i32_16x16x64_i8 v[8:11], v[166:169], v[206:209], v[8:11]
	v_mfma_i32_16x16x64_i8 v[0:3], v[174:177], v[206:209], v[0:3]
	v_mfma_i32_16x16x64_i8 v[56:59], v[170:173], v[186:189], v[56:59]
	v_mfma_i32_16x16x64_i8 v[48:51], v[178:181], v[186:189], v[48:51]
	v_mfma_i32_16x16x64_i8 v[40:43], v[170:173], v[194:197], v[40:43]
	v_mfma_i32_16x16x64_i8 v[32:35], v[178:181], v[194:197], v[32:35]
	v_mfma_i32_16x16x64_i8 v[24:27], v[170:173], v[202:205], v[24:27]
	v_mfma_i32_16x16x64_i8 v[16:19], v[178:181], v[202:205], v[16:19]
	v_mfma_i32_16x16x64_i8 v[8:11], v[170:173], v[210:213], v[8:11]
	v_mfma_i32_16x16x64_i8 v[0:3], v[178:181], v[210:213], v[0:3]
	s_setprio 0
	s_barrier
	s_add_i32 s53, 0, 0x18000
	s_add_i32 s54, 0, 0x1c000
	v_add_u32_e32 v162, s53, v153
	v_add_u32_e32 v178, s54, v153
	ds_read_b128 v[144:147], v162
	ds_read_b128 v[148:151], v162 offset:1024
	ds_read_b128 v[158:161], v162 offset:2048
	ds_read_b128 v[162:165], v162 offset:3072
	ds_read_b128 v[166:169], v178
	ds_read_b128 v[170:173], v178 offset:1024
	ds_read_b128 v[174:177], v178 offset:2048
	ds_read_b128 v[178:181], v178 offset:3072
	s_add_u32 s38, s38, 0x80000
	s_addc_u32 s39, s39, 0
	s_mov_b32 m0, s33
	v_lshl_add_u64 v[222:223], s[38:39], 0, v[134:135]
	ds_read_b128 v[182:185], v157 offset:32768
	ds_read_b128 v[186:189], v157 offset:33792
	ds_read_b128 v[190:193], v157 offset:34816
	ds_read_b128 v[194:197], v157 offset:35840
	ds_read_b128 v[198:201], v157 offset:36864
	ds_read_b128 v[202:205], v157 offset:37888
	ds_read_b128 v[206:209], v157 offset:38912
	ds_read_b128 v[210:213], v157 offset:39936
	global_load_lds_dwordx4 v[222:223], off
	v_lshl_add_u64 v[222:223], s[38:39], 0, v[130:131]
	s_mov_b32 m0, s35
	s_nop 0
	global_load_lds_dwordx4 v[222:223], off
	s_nop 0
	s_waitcnt vmcnt(8)
	s_waitcnt lgkmcnt(0)
	s_barrier
	s_setprio 1
	s_waitcnt lgkmcnt(0)
	v_mfma_i32_16x16x64_i8 v[124:127], v[144:147], v[182:185], v[124:127]
	v_mfma_i32_16x16x64_i8 v[116:119], v[158:161], v[182:185], v[116:119]
	v_mfma_i32_16x16x64_i8 v[108:111], v[144:147], v[190:193], v[108:111]
	v_mfma_i32_16x16x64_i8 v[100:103], v[158:161], v[190:193], v[100:103]
	v_mfma_i32_16x16x64_i8 v[92:95], v[144:147], v[198:201], v[92:95]
	v_mfma_i32_16x16x64_i8 v[84:87], v[158:161], v[198:201], v[84:87]
	v_mfma_i32_16x16x64_i8 v[76:79], v[144:147], v[206:209], v[76:79]
	v_mfma_i32_16x16x64_i8 v[68:71], v[158:161], v[206:209], v[68:71]
	v_mfma_i32_16x16x64_i8 v[124:127], v[148:151], v[186:189], v[124:127]
	v_mfma_i32_16x16x64_i8 v[116:119], v[162:165], v[186:189], v[116:119]
	v_mfma_i32_16x16x64_i8 v[108:111], v[148:151], v[194:197], v[108:111]
	v_mfma_i32_16x16x64_i8 v[100:103], v[162:165], v[194:197], v[100:103]
	v_mfma_i32_16x16x64_i8 v[92:95], v[148:151], v[202:205], v[92:95]
	v_mfma_i32_16x16x64_i8 v[84:87], v[162:165], v[202:205], v[84:87]
	v_mfma_i32_16x16x64_i8 v[76:79], v[148:151], v[210:213], v[76:79]
	v_mfma_i32_16x16x64_i8 v[68:71], v[162:165], v[210:213], v[68:71]
	s_setprio 0
	s_setprio 1
	v_mfma_i32_16x16x64_i8 v[120:123], v[166:169], v[182:185], v[120:123]
	v_mfma_i32_16x16x64_i8 v[112:115], v[174:177], v[182:185], v[112:115]
	v_mfma_i32_16x16x64_i8 v[104:107], v[166:169], v[190:193], v[104:107]
	v_mfma_i32_16x16x64_i8 v[96:99], v[174:177], v[190:193], v[96:99]
	v_mfma_i32_16x16x64_i8 v[88:91], v[166:169], v[198:201], v[88:91]
	v_mfma_i32_16x16x64_i8 v[80:83], v[174:177], v[198:201], v[80:83]
	v_mfma_i32_16x16x64_i8 v[72:75], v[166:169], v[206:209], v[72:75]
	v_mfma_i32_16x16x64_i8 v[64:67], v[174:177], v[206:209], v[64:67]
	v_mfma_i32_16x16x64_i8 v[120:123], v[170:173], v[186:189], v[120:123]
	v_mfma_i32_16x16x64_i8 v[112:115], v[178:181], v[186:189], v[112:115]
	v_mfma_i32_16x16x64_i8 v[104:107], v[170:173], v[194:197], v[104:107]
	v_mfma_i32_16x16x64_i8 v[96:99], v[178:181], v[194:197], v[96:99]
	v_mfma_i32_16x16x64_i8 v[88:91], v[170:173], v[202:205], v[88:91]
	v_mfma_i32_16x16x64_i8 v[80:83], v[178:181], v[202:205], v[80:83]
	v_mfma_i32_16x16x64_i8 v[72:75], v[170:173], v[210:213], v[72:75]
	v_mfma_i32_16x16x64_i8 v[64:67], v[178:181], v[210:213], v[64:67]
	s_setprio 0
	s_barrier
	s_add_i32 s38, s53, s2
	v_lshl_add_u64 v[214:215], v[214:215], 0, s[12:13]
	s_mov_b32 m0, s38
	ds_read_b128 v[182:185], v157 offset:49152
	ds_read_b128 v[186:189], v157 offset:50176
	ds_read_b128 v[190:193], v157 offset:51200
	ds_read_b128 v[194:197], v157 offset:52224
	ds_read_b128 v[198:201], v157 offset:53248
	ds_read_b128 v[202:205], v157 offset:54272
	ds_read_b128 v[206:209], v157 offset:55296
	ds_read_b128 v[210:213], v157 offset:56320
	global_load_lds_dwordx4 v[214:215], off
	s_add_i32 m0, s38, 0x2000
	s_add_u32 s36, s36, 0x80080
	v_lshl_add_u64 v[214:215], v[216:217], 0, s[12:13]
	s_addc_u32 s37, s37, 0
	s_add_i32 s38, s54, s2
	global_load_lds_dwordx4 v[214:215], off
	v_lshl_add_u64 v[214:215], s[36:37], 0, v[132:133]
	s_mov_b32 m0, s38
	s_nop 0
	global_load_lds_dwordx4 v[214:215], off
	v_lshl_add_u64 v[214:215], s[36:37], 0, v[128:129]
	s_add_i32 m0, s38, 0x2000
	s_nop 0
	global_load_lds_dwordx4 v[214:215], off
	v_lshl_add_u64 v[214:215], v[218:219], 0, s[12:13]
	s_mov_b32 m0, s42
	s_nop 0
	global_load_lds_dwordx4 v[214:215], off
	v_lshl_add_u64 v[214:215], v[220:221], 0, s[12:13]
	s_mov_b32 m0, s43
	s_nop 0
	global_load_lds_dwordx4 v[214:215], off
	s_waitcnt vmcnt(8)
	s_waitcnt lgkmcnt(0)
	s_barrier
	s_setprio 1
	s_waitcnt lgkmcnt(0)
	v_mfma_i32_16x16x64_i8 v[60:63], v[144:147], v[182:185], v[60:63]
	v_mfma_i32_16x16x64_i8 v[52:55], v[158:161], v[182:185], v[52:55]
	v_mfma_i32_16x16x64_i8 v[44:47], v[144:147], v[190:193], v[44:47]
	v_mfma_i32_16x16x64_i8 v[36:39], v[158:161], v[190:193], v[36:39]
	v_mfma_i32_16x16x64_i8 v[28:31], v[144:147], v[198:201], v[28:31]
	v_mfma_i32_16x16x64_i8 v[20:23], v[158:161], v[198:201], v[20:23]
	v_mfma_i32_16x16x64_i8 v[12:15], v[144:147], v[206:209], v[12:15]
	v_mfma_i32_16x16x64_i8 v[4:7], v[158:161], v[206:209], v[4:7]
	v_mfma_i32_16x16x64_i8 v[60:63], v[148:151], v[186:189], v[60:63]
	v_mfma_i32_16x16x64_i8 v[52:55], v[162:165], v[186:189], v[52:55]
	v_mfma_i32_16x16x64_i8 v[44:47], v[148:151], v[194:197], v[44:47]
	v_mfma_i32_16x16x64_i8 v[36:39], v[162:165], v[194:197], v[36:39]
	v_mfma_i32_16x16x64_i8 v[28:31], v[148:151], v[202:205], v[28:31]
	v_mfma_i32_16x16x64_i8 v[20:23], v[162:165], v[202:205], v[20:23]
	v_mfma_i32_16x16x64_i8 v[12:15], v[148:151], v[210:213], v[12:15]
	v_mfma_i32_16x16x64_i8 v[4:7], v[162:165], v[210:213], v[4:7]
	s_setprio 0
	s_setprio 1
	v_mfma_i32_16x16x64_i8 v[56:59], v[166:169], v[182:185], v[56:59]
	v_mfma_i32_16x16x64_i8 v[48:51], v[174:177], v[182:185], v[48:51]
	v_mfma_i32_16x16x64_i8 v[40:43], v[166:169], v[190:193], v[40:43]
	v_mfma_i32_16x16x64_i8 v[32:35], v[174:177], v[190:193], v[32:35]
	v_mfma_i32_16x16x64_i8 v[24:27], v[166:169], v[198:201], v[24:27]
	v_mfma_i32_16x16x64_i8 v[16:19], v[174:177], v[198:201], v[16:19]
	v_mfma_i32_16x16x64_i8 v[8:11], v[166:169], v[206:209], v[8:11]
	v_mfma_i32_16x16x64_i8 v[0:3], v[174:177], v[206:209], v[0:3]
	v_mfma_i32_16x16x64_i8 v[56:59], v[170:173], v[186:189], v[56:59]
	v_mfma_i32_16x16x64_i8 v[48:51], v[178:181], v[186:189], v[48:51]
	v_mfma_i32_16x16x64_i8 v[40:43], v[170:173], v[194:197], v[40:43]
	v_mfma_i32_16x16x64_i8 v[32:35], v[178:181], v[194:197], v[32:35]
	v_mfma_i32_16x16x64_i8 v[24:27], v[170:173], v[202:205], v[24:27]
	v_mfma_i32_16x16x64_i8 v[16:19], v[178:181], v[202:205], v[16:19]
	v_mfma_i32_16x16x64_i8 v[8:11], v[170:173], v[210:213], v[8:11]
	v_mfma_i32_16x16x64_i8 v[0:3], v[178:181], v[210:213], v[0:3]
	s_setprio 0
	s_barrier
	s_add_i32 s52, s52, 2
	s_add_u32 s30, s30, 0x100
	s_addc_u32 s31, s31, 0
	s_add_u32 s50, s50, 0x100
	s_addc_u32 s51, s51, 0
	s_cmp_gt_u32 s52, 29
	s_cbranch_scc0 .LBB0_773
	s_and_b64 vcc, exec, s[14:15]
	s_cbranch_vccz .LBB0_776
	s_barrier

.LBB0_858:
	ds_read_b128 v[152:155], v149
	ds_read_b128 v[156:159], v149 offset:1024
	ds_read_b128 v[160:163], v149 offset:2048
	ds_read_b128 v[164:167], v149 offset:3072
	ds_read_b128 v[168:171], v150
	ds_read_b128 v[172:175], v150 offset:1024
	ds_read_b128 v[176:179], v150 offset:2048
	ds_read_b128 v[180:183], v150 offset:3072
	s_add_u32 s26, s24, 0x100
	s_addc_u32 s27, s25, 0
	s_cmpk_eq_i32 s54, 0xa8
	s_cselect_b32 s31, s5, s27
	s_cselect_b32 s30, s4, s26
	s_cselect_b32 s29, s23, s53
	s_cselect_b32 s28, s22, s52
	v_lshl_add_u64 v[144:145], s[24:25], 0, v[136:137]
	s_add_i32 m0, s33, 0xc000
	ds_read_b128 v[184:187], v151
	ds_read_b128 v[188:191], v151 offset:1024
	ds_read_b128 v[192:195], v151 offset:2048
	ds_read_b128 v[196:199], v151 offset:3072
	ds_read_b128 v[200:203], v151 offset:4096
	ds_read_b128 v[204:207], v151 offset:5120
	ds_read_b128 v[208:211], v151 offset:6144
	ds_read_b128 v[212:215], v151 offset:7168
	global_load_lds_dwordx4 v[144:145], off
	v_lshl_add_u64 v[144:145], s[24:25], 0, v[138:139]
	s_add_i32 m0, s33, 0xe000
	s_nop 0
	global_load_lds_dwordx4 v[144:145], off
	s_nop 0
	s_waitcnt vmcnt(8)
	s_waitcnt lgkmcnt(0)
	s_barrier
	s_setprio 1
	s_waitcnt lgkmcnt(0)
	v_mfma_f32_16x16x32_bf16 v[124:127], v[152:155], v[184:187], v[124:127]
	v_mfma_f32_16x16x32_bf16 v[120:123], v[160:163], v[184:187], v[120:123]
	v_mfma_f32_16x16x32_bf16 v[116:119], v[152:155], v[192:195], v[116:119]
	v_mfma_f32_16x16x32_bf16 v[108:111], v[160:163], v[192:195], v[108:111]
	v_mfma_f32_16x16x32_bf16 v[100:103], v[152:155], v[200:203], v[100:103]
	v_mfma_f32_16x16x32_bf16 v[92:95], v[160:163], v[200:203], v[92:95]
	v_mfma_f32_16x16x32_bf16 v[84:87], v[152:155], v[208:211], v[84:87]
	v_mfma_f32_16x16x32_bf16 v[76:79], v[160:163], v[208:211], v[76:79]
	v_mfma_f32_16x16x32_bf16 v[124:127], v[156:159], v[188:191], v[124:127]
	v_mfma_f32_16x16x32_bf16 v[120:123], v[164:167], v[188:191], v[120:123]
	v_mfma_f32_16x16x32_bf16 v[116:119], v[156:159], v[196:199], v[116:119]
	v_mfma_f32_16x16x32_bf16 v[108:111], v[164:167], v[196:199], v[108:111]
	v_mfma_f32_16x16x32_bf16 v[100:103], v[156:159], v[204:207], v[100:103]
	v_mfma_f32_16x16x32_bf16 v[92:95], v[164:167], v[204:207], v[92:95]
	v_mfma_f32_16x16x32_bf16 v[84:87], v[156:159], v[212:215], v[84:87]
	v_mfma_f32_16x16x32_bf16 v[76:79], v[164:167], v[212:215], v[76:79]
	s_setprio 0
	s_setprio 1
	v_mfma_f32_16x16x32_bf16 v[112:115], v[168:171], v[184:187], v[112:115]
	v_mfma_f32_16x16x32_bf16 v[104:107], v[176:179], v[184:187], v[104:107]
	v_mfma_f32_16x16x32_bf16 v[96:99], v[168:171], v[192:195], v[96:99]
	v_mfma_f32_16x16x32_bf16 v[88:91], v[176:179], v[192:195], v[88:91]
	v_mfma_f32_16x16x32_bf16 v[80:83], v[168:171], v[200:203], v[80:83]
	v_mfma_f32_16x16x32_bf16 v[72:75], v[176:179], v[200:203], v[72:75]
	v_mfma_f32_16x16x32_bf16 v[68:71], v[168:171], v[208:211], v[68:71]
	v_mfma_f32_16x16x32_bf16 v[64:67], v[176:179], v[208:211], v[64:67]
	v_mfma_f32_16x16x32_bf16 v[112:115], v[172:175], v[188:191], v[112:115]
	v_mfma_f32_16x16x32_bf16 v[104:107], v[180:183], v[188:191], v[104:107]
	v_mfma_f32_16x16x32_bf16 v[96:99], v[172:175], v[196:199], v[96:99]
	v_mfma_f32_16x16x32_bf16 v[88:91], v[180:183], v[196:199], v[88:91]
	v_mfma_f32_16x16x32_bf16 v[80:83], v[172:175], v[204:207], v[80:83]
	v_mfma_f32_16x16x32_bf16 v[72:75], v[180:183], v[204:207], v[72:75]
	v_mfma_f32_16x16x32_bf16 v[68:71], v[172:175], v[212:215], v[68:71]
	v_mfma_f32_16x16x32_bf16 v[64:67], v[180:183], v[212:215], v[64:67]
	s_setprio 0
	s_barrier
	s_add_i32 s24, s42, s2
	v_lshl_add_u64 v[144:145], s[28:29], 0, v[132:133]
	s_mov_b32 m0, s24
	ds_read_b128 v[184:187], v151 offset:16384
	ds_read_b128 v[188:191], v151 offset:17408
	ds_read_b128 v[192:195], v151 offset:18432
	ds_read_b128 v[196:199], v151 offset:19456
	ds_read_b128 v[200:203], v151 offset:20480
	ds_read_b128 v[204:207], v151 offset:21504
	ds_read_b128 v[208:211], v151 offset:22528
	ds_read_b128 v[212:215], v151 offset:23552
	global_load_lds_dwordx4 v[144:145], off
	s_add_i32 m0, s24, 0x2000
	s_add_u32 s24, s28, 0x2b0000
	v_lshl_add_u64 v[216:217], s[28:29], 0, v[128:129]
	s_addc_u32 s25, s29, 0
	s_add_i32 s55, s43, s2
	global_load_lds_dwordx4 v[216:217], off
	v_lshl_add_u64 v[218:219], s[24:25], 0, v[132:133]
	s_mov_b32 m0, s55
	v_lshl_add_u64 v[220:221], s[30:31], 0, v[130:131]
	global_load_lds_dwordx4 v[218:219], off
	v_lshl_add_u64 v[218:219], s[24:25], 0, v[128:129]
	s_add_i32 m0, s55, 0x2000
	s_nop 0
	global_load_lds_dwordx4 v[218:219], off
	v_lshl_add_u64 v[218:219], s[30:31], 0, v[134:135]
	s_mov_b32 m0, s33
	s_nop 0
	global_load_lds_dwordx4 v[218:219], off
	s_mov_b32 m0, s35
	s_nop 0
	global_load_lds_dwordx4 v[220:221], off
	s_nop 0
	s_waitcnt vmcnt(8)
	s_waitcnt lgkmcnt(0)
	s_barrier
	s_setprio 1
	s_waitcnt lgkmcnt(0)
	v_mfma_f32_16x16x32_bf16 v[60:63], v[152:155], v[184:187], v[60:63]
	v_mfma_f32_16x16x32_bf16 v[56:59], v[160:163], v[184:187], v[56:59]
	v_mfma_f32_16x16x32_bf16 v[52:55], v[152:155], v[192:195], v[52:55]
	v_mfma_f32_16x16x32_bf16 v[44:47], v[160:163], v[192:195], v[44:47]
	v_mfma_f32_16x16x32_bf16 v[36:39], v[152:155], v[200:203], v[36:39]
	v_mfma_f32_16x16x32_bf16 v[28:31], v[160:163], v[200:203], v[28:31]
	v_mfma_f32_16x16x32_bf16 v[20:23], v[152:155], v[208:211], v[20:23]
	v_mfma_f32_16x16x32_bf16 v[12:15], v[160:163], v[208:211], v[12:15]
	v_mfma_f32_16x16x32_bf16 v[60:63], v[156:159], v[188:191], v[60:63]
	v_mfma_f32_16x16x32_bf16 v[56:59], v[164:167], v[188:191], v[56:59]
	v_mfma_f32_16x16x32_bf16 v[52:55], v[156:159], v[196:199], v[52:55]
	v_mfma_f32_16x16x32_bf16 v[44:47], v[164:167], v[196:199], v[44:47]
	v_mfma_f32_16x16x32_bf16 v[36:39], v[156:159], v[204:207], v[36:39]
	v_mfma_f32_16x16x32_bf16 v[28:31], v[164:167], v[204:207], v[28:31]
	v_mfma_f32_16x16x32_bf16 v[20:23], v[156:159], v[212:215], v[20:23]
	v_mfma_f32_16x16x32_bf16 v[12:15], v[164:167], v[212:215], v[12:15]
	s_setprio 0
	s_setprio 1
	v_mfma_f32_16x16x32_bf16 v[48:51], v[168:171], v[184:187], v[48:51]
	v_mfma_f32_16x16x32_bf16 v[40:43], v[176:179], v[184:187], v[40:43]
	v_mfma_f32_16x16x32_bf16 v[32:35], v[168:171], v[192:195], v[32:35]
	v_mfma_f32_16x16x32_bf16 v[24:27], v[176:179], v[192:195], v[24:27]
	v_mfma_f32_16x16x32_bf16 v[16:19], v[168:171], v[200:203], v[16:19]
	v_mfma_f32_16x16x32_bf16 v[8:11], v[176:179], v[200:203], v[8:11]
	v_mfma_f32_16x16x32_bf16 v[4:7], v[168:171], v[208:211], v[4:7]
	v_mfma_f32_16x16x32_bf16 v[0:3], v[176:179], v[208:211], v[0:3]
	v_mfma_f32_16x16x32_bf16 v[48:51], v[172:175], v[188:191], v[48:51]
	v_mfma_f32_16x16x32_bf16 v[40:43], v[180:183], v[188:191], v[40:43]
	v_mfma_f32_16x16x32_bf16 v[32:35], v[172:175], v[196:199], v[32:35]
	v_mfma_f32_16x16x32_bf16 v[24:27], v[180:183], v[196:199], v[24:27]
	v_mfma_f32_16x16x32_bf16 v[16:19], v[172:175], v[204:207], v[16:19]
	v_mfma_f32_16x16x32_bf16 v[8:11], v[180:183], v[204:207], v[8:11]
	v_mfma_f32_16x16x32_bf16 v[4:7], v[172:175], v[212:215], v[4:7]
	v_mfma_f32_16x16x32_bf16 v[0:3], v[180:183], v[212:215], v[0:3]
	s_setprio 0
	s_barrier
	s_add_i32 s55, 0, 0x18000
	s_add_i32 s58, 0, 0x1c000
	v_add_u32_e32 v164, s55, v147
	v_add_u32_e32 v180, s58, v147
	ds_read_b128 v[152:155], v164
	ds_read_b128 v[156:159], v164 offset:1024
	ds_read_b128 v[160:163], v164 offset:2048
	ds_read_b128 v[164:167], v164 offset:3072
	ds_read_b128 v[168:171], v180
	ds_read_b128 v[172:175], v180 offset:1024
	ds_read_b128 v[176:179], v180 offset:2048
	ds_read_b128 v[180:183], v180 offset:3072
	s_add_u32 s24, s30, 0x2b0000
	s_addc_u32 s25, s31, 0
	s_mov_b32 m0, s36
	v_lshl_add_u64 v[222:223], s[24:25], 0, v[134:135]
	ds_read_b128 v[184:187], v151 offset:32768
	ds_read_b128 v[188:191], v151 offset:33792
	ds_read_b128 v[192:195], v151 offset:34816
	ds_read_b128 v[196:199], v151 offset:35840
	ds_read_b128 v[200:203], v151 offset:36864
	ds_read_b128 v[204:207], v151 offset:37888
	ds_read_b128 v[208:211], v151 offset:38912
	ds_read_b128 v[212:215], v151 offset:39936
	global_load_lds_dwordx4 v[222:223], off
	v_lshl_add_u64 v[222:223], s[24:25], 0, v[130:131]
	s_mov_b32 m0, s37
	s_nop 0
	global_load_lds_dwordx4 v[222:223], off
	s_nop 0
	s_waitcnt vmcnt(8)
	s_waitcnt lgkmcnt(0)
	s_barrier
	s_setprio 1
	s_waitcnt lgkmcnt(0)
	v_mfma_f32_16x16x32_bf16 v[124:127], v[152:155], v[184:187], v[124:127]
	v_mfma_f32_16x16x32_bf16 v[120:123], v[160:163], v[184:187], v[120:123]
	v_mfma_f32_16x16x32_bf16 v[116:119], v[152:155], v[192:195], v[116:119]
	v_mfma_f32_16x16x32_bf16 v[108:111], v[160:163], v[192:195], v[108:111]
	v_mfma_f32_16x16x32_bf16 v[100:103], v[152:155], v[200:203], v[100:103]
	v_mfma_f32_16x16x32_bf16 v[92:95], v[160:163], v[200:203], v[92:95]
	v_mfma_f32_16x16x32_bf16 v[84:87], v[152:155], v[208:211], v[84:87]
	v_mfma_f32_16x16x32_bf16 v[76:79], v[160:163], v[208:211], v[76:79]
	v_mfma_f32_16x16x32_bf16 v[124:127], v[156:159], v[188:191], v[124:127]
	v_mfma_f32_16x16x32_bf16 v[120:123], v[164:167], v[188:191], v[120:123]
	v_mfma_f32_16x16x32_bf16 v[116:119], v[156:159], v[196:199], v[116:119]
	v_mfma_f32_16x16x32_bf16 v[108:111], v[164:167], v[196:199], v[108:111]
	v_mfma_f32_16x16x32_bf16 v[100:103], v[156:159], v[204:207], v[100:103]
	v_mfma_f32_16x16x32_bf16 v[92:95], v[164:167], v[204:207], v[92:95]
	v_mfma_f32_16x16x32_bf16 v[84:87], v[156:159], v[212:215], v[84:87]
	v_mfma_f32_16x16x32_bf16 v[76:79], v[164:167], v[212:215], v[76:79]
	s_setprio 0
	s_setprio 1
	v_mfma_f32_16x16x32_bf16 v[112:115], v[168:171], v[184:187], v[112:115]
	v_mfma_f32_16x16x32_bf16 v[104:107], v[176:179], v[184:187], v[104:107]
	v_mfma_f32_16x16x32_bf16 v[96:99], v[168:171], v[192:195], v[96:99]
	v_mfma_f32_16x16x32_bf16 v[88:91], v[176:179], v[192:195], v[88:91]
	v_mfma_f32_16x16x32_bf16 v[80:83], v[168:171], v[200:203], v[80:83]
	v_mfma_f32_16x16x32_bf16 v[72:75], v[176:179], v[200:203], v[72:75]
	v_mfma_f32_16x16x32_bf16 v[68:71], v[168:171], v[208:211], v[68:71]
	v_mfma_f32_16x16x32_bf16 v[64:67], v[176:179], v[208:211], v[64:67]
	v_mfma_f32_16x16x32_bf16 v[112:115], v[172:175], v[188:191], v[112:115]
	v_mfma_f32_16x16x32_bf16 v[104:107], v[180:183], v[188:191], v[104:107]
	v_mfma_f32_16x16x32_bf16 v[96:99], v[172:175], v[196:199], v[96:99]
	v_mfma_f32_16x16x32_bf16 v[88:91], v[180:183], v[196:199], v[88:91]
	v_mfma_f32_16x16x32_bf16 v[80:83], v[172:175], v[204:207], v[80:83]
	v_mfma_f32_16x16x32_bf16 v[72:75], v[180:183], v[204:207], v[72:75]
	v_mfma_f32_16x16x32_bf16 v[68:71], v[172:175], v[212:215], v[68:71]
	v_mfma_f32_16x16x32_bf16 v[64:67], v[180:183], v[212:215], v[64:67]
	s_setprio 0
	s_barrier
	s_add_i32 s24, s55, s2
	v_lshl_add_u64 v[144:145], v[144:145], 0, s[8:9]
	s_mov_b32 m0, s24
	ds_read_b128 v[184:187], v151 offset:49152
	ds_read_b128 v[188:191], v151 offset:50176
	ds_read_b128 v[192:195], v151 offset:51200
	ds_read_b128 v[196:199], v151 offset:52224
	ds_read_b128 v[200:203], v151 offset:53248
	ds_read_b128 v[204:207], v151 offset:54272
	ds_read_b128 v[208:211], v151 offset:55296
	ds_read_b128 v[212:215], v151 offset:56320
	global_load_lds_dwordx4 v[144:145], off
	s_add_i32 m0, s24, 0x2000
	s_add_u32 s24, s28, 0x2b0080
	v_lshl_add_u64 v[144:145], v[216:217], 0, s[8:9]
	s_addc_u32 s25, s29, 0
	s_add_i32 s28, s58, s2
	global_load_lds_dwordx4 v[144:145], off
	v_lshl_add_u64 v[144:145], s[24:25], 0, v[132:133]
	s_mov_b32 m0, s28
	s_nop 0
	global_load_lds_dwordx4 v[144:145], off
	v_lshl_add_u64 v[144:145], s[24:25], 0, v[128:129]
	s_add_i32 m0, s28, 0x2000
	s_nop 0
	global_load_lds_dwordx4 v[144:145], off
	v_lshl_add_u64 v[144:145], v[218:219], 0, s[8:9]
	s_mov_b32 m0, s40
	s_nop 0
	global_load_lds_dwordx4 v[144:145], off
	v_lshl_add_u64 v[144:145], v[220:221], 0, s[8:9]
	s_mov_b32 m0, s41
	s_nop 0
	global_load_lds_dwordx4 v[144:145], off
	s_waitcnt vmcnt(8)
	s_waitcnt lgkmcnt(0)
	s_barrier
	s_setprio 1
	s_waitcnt lgkmcnt(0)
	v_mfma_f32_16x16x32_bf16 v[60:63], v[152:155], v[184:187], v[60:63]
	v_mfma_f32_16x16x32_bf16 v[56:59], v[160:163], v[184:187], v[56:59]
	v_mfma_f32_16x16x32_bf16 v[52:55], v[152:155], v[192:195], v[52:55]
	v_mfma_f32_16x16x32_bf16 v[44:47], v[160:163], v[192:195], v[44:47]
	v_mfma_f32_16x16x32_bf16 v[36:39], v[152:155], v[200:203], v[36:39]
	v_mfma_f32_16x16x32_bf16 v[28:31], v[160:163], v[200:203], v[28:31]
	v_mfma_f32_16x16x32_bf16 v[20:23], v[152:155], v[208:211], v[20:23]
	v_mfma_f32_16x16x32_bf16 v[12:15], v[160:163], v[208:211], v[12:15]
	v_mfma_f32_16x16x32_bf16 v[60:63], v[156:159], v[188:191], v[60:63]
	v_mfma_f32_16x16x32_bf16 v[56:59], v[164:167], v[188:191], v[56:59]
	v_mfma_f32_16x16x32_bf16 v[52:55], v[156:159], v[196:199], v[52:55]
	v_mfma_f32_16x16x32_bf16 v[44:47], v[164:167], v[196:199], v[44:47]
	v_mfma_f32_16x16x32_bf16 v[36:39], v[156:159], v[204:207], v[36:39]
	v_mfma_f32_16x16x32_bf16 v[28:31], v[164:167], v[204:207], v[28:31]
	v_mfma_f32_16x16x32_bf16 v[20:23], v[156:159], v[212:215], v[20:23]
	v_mfma_f32_16x16x32_bf16 v[12:15], v[164:167], v[212:215], v[12:15]
	s_setprio 0
	s_setprio 1
	v_mfma_f32_16x16x32_bf16 v[48:51], v[168:171], v[184:187], v[48:51]
	v_mfma_f32_16x16x32_bf16 v[40:43], v[176:179], v[184:187], v[40:43]
	v_mfma_f32_16x16x32_bf16 v[32:35], v[168:171], v[192:195], v[32:35]
	v_mfma_f32_16x16x32_bf16 v[24:27], v[176:179], v[192:195], v[24:27]
	v_mfma_f32_16x16x32_bf16 v[16:19], v[168:171], v[200:203], v[16:19]
	v_mfma_f32_16x16x32_bf16 v[8:11], v[176:179], v[200:203], v[8:11]
	v_mfma_f32_16x16x32_bf16 v[4:7], v[168:171], v[208:211], v[4:7]
	v_mfma_f32_16x16x32_bf16 v[0:3], v[176:179], v[208:211], v[0:3]
	v_mfma_f32_16x16x32_bf16 v[48:51], v[172:175], v[188:191], v[48:51]
	v_mfma_f32_16x16x32_bf16 v[40:43], v[180:183], v[188:191], v[40:43]
	v_mfma_f32_16x16x32_bf16 v[32:35], v[172:175], v[196:199], v[32:35]
	v_mfma_f32_16x16x32_bf16 v[24:27], v[180:183], v[196:199], v[24:27]
	v_mfma_f32_16x16x32_bf16 v[16:19], v[172:175], v[204:207], v[16:19]
	v_mfma_f32_16x16x32_bf16 v[8:11], v[180:183], v[204:207], v[8:11]
	v_mfma_f32_16x16x32_bf16 v[4:7], v[172:175], v[212:215], v[4:7]
	v_mfma_f32_16x16x32_bf16 v[0:3], v[180:183], v[212:215], v[0:3]
	s_setprio 0
	s_barrier
	s_add_i32 s54, s54, 2
	s_add_u32 s52, s52, 0x100
	s_addc_u32 s53, s53, 0
	s_cmpk_gt_u32 s54, 0xa9
	s_mov_b64 s[24:25], s[26:27]
	s_cbranch_scc0 .LBB0_858
	s_and_b64 vcc, exec, s[10:11]
	s_cbranch_vccz .LBB0_861
	s_barrier
